# speedup vs baseline: 1.0181x; 1.0101x over previous
; DEV int ltid() { int t = threadIdx.x; asm volatile("" : "+v"(t)); return t; }
; DEV int v_st(int k, int c) { const int kk = (k & ~0xC) | ((k & 4) << 1) | ((k & 8) >> 1); return ((kk >> 3) * 4 + (c >> 5)) * 512 + ((kk & 7) * 32 + (c & 31)) * 2; }
; DEV int v_rd_base(int lane) { return ((lane & 3) << 3) | (((lane >> 2) & 3) << 6) | (((lane >> 4) & 1) << 5) | (((lane >> 5) & 1) << 8); }
; #define SLOAD(i, k0) do { sr_[i].vs0 = LD8(&Vh[(long)((k0) + sr) * LDK + sc]); sr_[i].vs1 = LD8(&Vh[(long)((k0) + 32 + sr) * LDK + sc]); \
;     sr_[i].ks0 = LD8(&Kh[(long)((k0) + sr) * LDK + sc]); sr_[i].ks1 = LD8(&Kh[(long)((k0) + 32 + sr) * LDK + sc]); \
;     sr_[i].kp = LD8(&KPh[(long)((k0) + pr) * LDKP + pc]); } while (0)
; DEV void attn_item(const u16* __restrict__ Qb, const u16* __restrict__ Kh, const u16* __restrict__ Vh, const u16* __restrict__ KPh,
;                    u16* __restrict__ Ob, int seq, char* lds) {
;   const int tid = ltid(), wid = tid >> 6, lane = tid & 63, r32 = lane & 31, hi = lane >> 5;
;   char* V_lds = lds; char* K_lds = lds + 2 * SHM_V; char* KP_lds = lds + 2 * SHM_V + 2 * SHM_K;
;   float* wsf = (float*)(lds + 2 * SHM_V + 2 * SHM_K + 2 * SHM_KP) + wid * 64; float* li_l = wsf; float* al_l = wsf + 32;
;   char* qpl = lds + 2 * SHM_V + 2 * SHM_K + 2 * SHM_KP + 2048 + wid * ((12 - NQR) * 1024) + lane * 16;
;   float m_reg = -1e30f, l_reg = 0; f32x16 o[4] = {}; bf16x8 qr[NQR];
;   const u16* Qw = Qb + (long)(wid * QBLK + r32) * LDQ + hi * 8;
; #pragma unroll
;   for (int d0 = 0; d0 < NQR; ++d0) qr[d0] = *reinterpret_cast<const bf16x8*>(Qw + d0 * 16);
; #pragma unroll
;   for (int d1 = NQR; d1 < 12; ++d1) *reinterpret_cast<bf16x8*>(qpl + (d1 - NQR) * 1024) = *reinterpret_cast<const bf16x8*>(Qw + d1 * 16);
;   const int sr = tid >> 4, sc = (tid & 15) * 8, vst0 = v_st(sr, sc), vst1 = v_st(32 + sr, sc);
;   const int pr = tid >> 3, pc = (tid & 7) * 8, kpst = KPSWZ(pr, pc * 2);
;   const int vb0 = (int)(uintptr_t)V_lds + v_rd_base(lane);
;   struct { bf16x8 vs0, vs1, ks0, ks1, kp; } sr_[1];
;     ...
;   f32x16 pA0, pA1, pB0, pB1; float mnA, mnB, alA, alB; bf16x8 pa0, pa1, pa2, pa3; const int NT = seq / KVBLK;
;   constexpr int SE = 0, SO = 0;
;   SLOAD(SE, 0); asm volatile("s_waitcnt vmcnt(0)" ::: "memory"); SWRITE(0, SE); __syncthreads();
.LBB0_303:
	s_mul_i32 s1, s35, 0x1800
	s_mul_hi_u32 s4, s34, 0x1800
	s_add_i32 s4, s4, s1
	s_mul_i32 s1, s34, 0x1800
	s_add_u32 s1, s20, s1
	s_mul_i32 s28, s0, 0xc0
	s_addc_u32 s7, s21, s4
	s_lshl_b64 s[4:5], s[28:29], 1
	s_add_u32 s6, s1, s4
	s_addc_u32 s7, s7, s5
	s_lshl_b64 s[4:5], s[54:55], 13
	v_mov_b32_e32 v50, v164
	s_barrier
	s_add_u32 s1, s24, s4
	s_addc_u32 s5, s25, s5
	v_ashrrev_i32_e32 v51, 6, v50
	s_lshl_b32 s28, s0, 8
	v_and_b32_e32 v148, 31, v50
	v_lshlrev_b32_e32 v138, 5, v51
	s_lshl_b64 s[62:63], s[28:29], 1
	v_bfe_u32 v149, v50, 5, 1
	v_or_b32_e32 v2, v138, v148
	v_mov_b64_e32 v[0:1], s[6:7]
	s_movk_i32 s0, 0x1800
	s_add_u32 s4, s1, s62
	v_mad_i64_i32 v[0:1], s[0:1], v2, s0, v[0:1]
	v_lshlrev_b32_e32 v136, 4, v149
	v_lshl_add_u64 v[46:47], v[0:1], 0, v[136:137]
	global_load_dwordx4 v[6:9], v[46:47], off offset:128
	global_load_dwordx4 v[10:13], v[46:47], off offset:160
	global_load_dwordx4 v[14:17], v[46:47], off offset:192
	global_load_dwordx4 v[18:21], v[46:47], off offset:224
	global_load_dwordx4 v[22:25], v[46:47], off offset:256
	global_load_dwordx4 v[26:29], v[46:47], off offset:288
	global_load_dwordx4 v[30:33], v[46:47], off offset:320
	global_load_dwordx4 v[34:37], v[46:47], off offset:352
	v_ashrrev_i32_e32 v48, 4, v50
	v_lshlrev_b32_e32 v66, 3, v50
	v_add_u32_e32 v64, 32, v48
	s_mul_i32 s0, s55, 0x880
	s_mul_hi_u32 s1, s54, 0x880
	v_and_b32_e32 v0, 0x78, v66
	v_ashrrev_i32_e32 v49, 31, v48
	v_ashrrev_i32_e32 v65, 31, v64
	s_addc_u32 s5, s5, s63
	s_add_i32 s1, s1, s0
	s_mul_i32 s6, s54, 0x880
	v_lshlrev_b32_e32 v67, 1, v0
	v_lshlrev_b64 v[2:3], 13, v[48:49]
	v_lshlrev_b64 v[4:5], 13, v[64:65]
	s_add_u32 s6, s22, s6
	v_or_b32_e32 v2, v2, v67
	v_or_b32_e32 v4, v4, v67
	s_addc_u32 s7, s23, s1
	v_lshl_add_u64 v[2:3], s[4:5], 0, v[2:3]
	v_lshl_add_u64 v[4:5], s[4:5], 0, v[4:5]
	v_ashrrev_i32_e32 v76, 3, v50
	v_lshlrev_b32_e32 v0, 4, v50
	global_load_dwordx4 v[38:41], v[2:3], off offset:256
	global_load_dwordx4 v[42:45], v[4:5], off offset:256
	global_load_dwordx4 v[52:55], v[2:3], off
	global_load_dwordx4 v[56:59], v[4:5], off
	v_mov_b64_e32 v[4:5], s[6:7]
	v_and_b32_e32 v0, 0x70, v0
	v_mad_i64_i32 v[60:61], s[4:5], v76, s71, v[4:5]
	v_mov_b32_e32 v1, v137
	v_lshl_add_u64 v[60:61], v[60:61], 0, v[0:1]
	global_load_dwordx4 v[60:63], v[60:61], off offset:2048
	s_nop 0
	global_load_dwordx4 v[108:111], v[46:47], off
	global_load_dwordx4 v[104:107], v[46:47], off offset:32
	global_load_dwordx4 v[100:103], v[46:47], off offset:64
	global_load_dwordx4 v[96:99], v[46:47], off offset:96
	v_and_b32_e32 v82, 63, v50
	v_lshlrev_b32_e32 v83, 4, v82
	v_lshl_add_u32 v51, v51, 13, v145
	v_and_b32_e32 v65, 0xfffff0, v48
	v_lshlrev_b32_e32 v68, 1, v48
	v_or_b32_e32 v77, v51, v83
	v_or_b32_e32 v78, 64, v136
	v_or_b32_e32 v79, 0x60, v136
	v_and_b32_e32 v85, 0x70, v66
	s_mov_b64 s[4:5], 0x80000
	v_and_b32_e32 v80, 0x3fffffc0, v50
	v_lshl_add_u32 v139, v80, 2, v144
	s_mov_b32 s6, s29
	s_mov_b32 s7, s29
	s_mov_b32 s8, s29
	s_mov_b32 s9, s29
	s_mov_b32 s10, s29
	s_mov_b32 s11, s29
	s_mov_b32 s12, s29
	s_mov_b32 s13, s29
	s_mov_b32 s14, s29
	s_mov_b32 s15, s29
	s_mov_b32 s16, s29
	s_mov_b32 s17, s29
	s_mov_b32 s18, s29
	s_waitcnt vmcnt(16)
	ds_write_b128 v77, v[6:9]
	s_waitcnt vmcnt(15)
	ds_write_b128 v77, v[10:13] offset:1024
	s_waitcnt vmcnt(14)
	ds_write_b128 v77, v[14:17] offset:2048
	s_waitcnt vmcnt(13)
	ds_write_b128 v77, v[18:21] offset:3072
	s_waitcnt vmcnt(12)
	ds_write_b128 v77, v[22:25] offset:4096
	s_waitcnt vmcnt(11)
	ds_write_b128 v77, v[26:29] offset:5120
	s_waitcnt vmcnt(10)
	ds_write_b128 v77, v[30:33] offset:6144
	s_waitcnt vmcnt(9)
	ds_write_b128 v77, v[34:37] offset:7168
	v_and_or_b32 v6, v68, 8, v65
	v_lshrrev_b32_e32 v7, 1, v48
	v_lshrrev_b32_e32 v6, 1, v6
	v_bfe_u32 v8, v66, 5, 2
	v_and_b32_e32 v9, 3, v48
	v_or_b32_e32 v6, v6, v8
	v_and_or_b32 v7, v7, 4, v9
	v_lshlrev_b32_e32 v6, 9, v6
	v_lshlrev_b32_e32 v7, 6, v7
	v_and_b32_e32 v9, 48, v67
	v_or3_b32 v154, v6, v7, v9
	v_and_b32_e32 v6, 0xfffff0, v64
	v_lshlrev_b32_e32 v10, 1, v64
	v_and_or_b32 v6, v10, 8, v6
	v_lshrrev_b32_e32 v6, 1, v6
	v_or_b32_e32 v6, v6, v8
	v_lshlrev_b32_e32 v6, 9, v6
	v_or3_b32 v155, v6, v7, v9
	v_lshlrev_b32_e32 v6, 7, v76
	v_and_b32_e32 v7, 0x70, v50
	v_bitop3_b32 v84, v0, v6, v7 bitop3:0xde
	v_lshlrev_b32_e32 v6, 8, v48
	v_and_b32_e32 v224, 0xf0, v50
	v_lshlrev_b32_e32 v225, 4, v50
	v_bitop3_b32 v156, v67, v6, v224 bitop3:0xde
	v_lshlrev_b32_e32 v6, 8, v64
	v_lshlrev_b32_e32 v14, 8, v148
	v_and_b32_e32 v225, 0xf0, v225
	v_bitop3_b32 v157, v67, v6, v224 bitop3:0xde
	v_add_u32_e32 v158, 0x10000, v84
	v_bitop3_b32 v159, v136, v14, v225 bitop3:0xde
	s_waitcnt vmcnt(0)
	s_waitcnt vmcnt(8)
	ds_write_b128 v154, v[38:41]
	s_waitcnt vmcnt(7)
	ds_write_b128 v155, v[42:45]
	s_waitcnt vmcnt(6)
	ds_write_b128 v156, v[52:55] offset:32768
	s_waitcnt vmcnt(5)
	ds_write_b128 v157, v[56:59] offset:32768
	s_waitcnt vmcnt(4)
	ds_write_b128 v158, v[60:63]
	s_waitcnt lgkmcnt(0)
	s_barrier
; #define SLOAD(i, k0) do { sr_[i].vs0 = LD8(&Vh[(long)((k0) + sr) * LDK + sc]); sr_[i].vs1 = LD8(&Vh[(long)((k0) + 32 + sr) * LDK + sc]); \
;     sr_[i].ks0 = LD8(&Kh[(long)((k0) + sr) * LDK + sc]); sr_[i].ks1 = LD8(&Kh[(long)((k0) + 32 + sr) * LDK + sc]); \
;     sr_[i].kp = LD8(&KPh[(long)((k0) + pr) * LDKP + pc]); } while (0)
; #define SWAIT() asm volatile("s_waitcnt vmcnt(0)" ::: "memory")
; DEV void qkt(f32x16& p0, f32x16& p1, const char* Ks, const char* KPs, const bf16x8* qr, const char* qpl, int r32, int hi) {
;   p0 = f32x16{}; p1 = f32x16{};
; #pragma unroll
;   for (int d0 = 0; d0 < 8; ++d0) { int cb = (d0 * 16 + hi * 8) * 2;
;     bf16x8 b0 = *reinterpret_cast<const bf16x8*>(Ks + KSWZ(r32, cb));
;     bf16x8 b1 = *reinterpret_cast<const bf16x8*>(Ks + KSWZ(32 + r32, cb));
;     bf16x8 qq = d0 < NQR ? qr[d0 < NQR ? d0 : 0] : *reinterpret_cast<const bf16x8*>(qpl + (d0 - NQR) * 1024);
;     p0 = __builtin_amdgcn_mfma_f32_32x32x16_bf16(b0, qq, p0, 0, 0, 0);
;     p1 = __builtin_amdgcn_mfma_f32_32x32x16_bf16(b1, qq, p1, 0, 0, 0); }
; #pragma unroll
;   for (int d1 = 0; d1 < 4; ++d1) { int cb = (d1 * 16 + hi * 8) * 2;
;     bf16x8 b0 = *reinterpret_cast<const bf16x8*>(KPs + KPSWZ(r32, cb));
;     bf16x8 b1 = *reinterpret_cast<const bf16x8*>(KPs + KPSWZ(32 + r32, cb));
;     bf16x8 qp = *reinterpret_cast<const bf16x8*>(qpl + (8 - NQR + d1) * 1024);
;     p0 = __builtin_amdgcn_mfma_f32_32x32x16_bf16(b0, qp, p0, 0, 0, 0);
;     p1 = __builtin_amdgcn_mfma_f32_32x32x16_bf16(b1, qp, p1, 0, 0, 0); }
; }
; DEV void attn_item(const u16* __restrict__ Qb, const u16* __restrict__ Kh, const u16* __restrict__ Vh, const u16* __restrict__ KPh,
;                    u16* __restrict__ Ob, int seq, char* lds) {
;     ...
;   qkt(pA0, pA1, K_lds, KP_lds, qr, qpl, r32, hi); partialSM(pA0, pA1, m_reg, mnA, alA);
;   SLOAD(SO, KVBLK);
;   SWAIT(); SWRITE(1, SO); __syncthreads();
	ds_read_b128 v[6:9], v159 offset:32768
	ds_read_b128 v[10:13], v159 offset:40960
	s_waitcnt vmcnt(3) lgkmcnt(1)
	v_mfma_f32_32x32x16_bf16 v[16:31], v[6:9], v[108:111], 0
	v_or_b32_e32 v15, 32, v136
	v_bitop3_b32 v162, v15, v14, v225 bitop3:0xde
	v_bitop3_b32 v163, v78, v14, v225 bitop3:0xde
	v_bitop3_b32 v166, v79, v14, v225 bitop3:0xde
	s_mov_b32 s19, s29
	v_add_u32_e32 v177, v51, v83
	s_mov_b32 s78, 2
	s_waitcnt lgkmcnt(0)
	v_mfma_f32_32x32x16_bf16 v[32:47], v[10:13], v[108:111], 0
	ds_read_b128 v[6:9], v162 offset:32768
	ds_read_b128 v[10:13], v162 offset:40960
	v_add_u32_e32 v183, 0x12000, v84
	v_lshl_or_b32 v150, v148, 2, v139
	v_mov_b32_e32 v151, 0
	s_waitcnt vmcnt(2) lgkmcnt(1)
	v_mfma_f32_32x32x16_bf16 v[16:31], v[6:9], v[104:107], v[16:31]
	s_waitcnt lgkmcnt(0)
	v_mfma_f32_32x32x16_bf16 v[32:47], v[10:13], v[104:107], v[32:47]
	ds_read_b128 v[6:9], v163 offset:32768
	ds_read_b128 v[10:13], v163 offset:40960
	s_waitcnt vmcnt(1) lgkmcnt(1)
	v_mfma_f32_32x32x16_bf16 v[16:31], v[6:9], v[100:103], v[16:31]
	s_waitcnt lgkmcnt(0)
	v_mfma_f32_32x32x16_bf16 v[32:47], v[10:13], v[100:103], v[32:47]
	ds_read_b128 v[6:9], v166 offset:32768
	ds_read_b128 v[10:13], v166 offset:40960
	s_waitcnt vmcnt(0) lgkmcnt(1)
	v_mfma_f32_32x32x16_bf16 v[16:31], v[6:9], v[96:99], v[16:31]
	v_or_b32_e32 v6, 0x80, v136
	v_bitop3_b32 v167, v6, v14, v225 bitop3:0xde
	s_waitcnt lgkmcnt(0)
	v_mfma_f32_32x32x16_bf16 v[32:47], v[10:13], v[96:99], v[32:47]
	ds_read_b128 v[6:9], v167 offset:32768
	ds_read_b128 v[10:13], v77
	ds_read_b128 v[52:55], v167 offset:40960
	ds_read_b128 v[56:59], v77 offset:1024
	s_waitcnt lgkmcnt(2)
	v_mfma_f32_32x32x16_bf16 v[16:31], v[6:9], v[10:13], v[16:31]
	v_or_b32_e32 v6, 0xa0, v136
	v_bitop3_b32 v168, v6, v14, v225 bitop3:0xde
	s_waitcnt lgkmcnt(1)
	v_mfma_f32_32x32x16_bf16 v[32:47], v[52:55], v[10:13], v[32:47]
	ds_read_b128 v[6:9], v168 offset:32768
	ds_read_b128 v[10:13], v168 offset:40960
	s_waitcnt lgkmcnt(1)
	v_mfma_f32_32x32x16_bf16 v[16:31], v[6:9], v[56:59], v[16:31]
	v_or_b32_e32 v6, 0xc0, v136
	v_bitop3_b32 v160, v6, v14, v225 bitop3:0xde
	s_waitcnt lgkmcnt(0)
	v_mfma_f32_32x32x16_bf16 v[32:47], v[10:13], v[56:59], v[32:47]
	ds_read_b128 v[6:9], v160 offset:32768
	ds_read_b128 v[10:13], v77 offset:2048
	ds_read_b128 v[52:55], v160 offset:40960
	ds_read_b128 v[56:59], v77 offset:3072
	s_waitcnt lgkmcnt(2)
	v_mfma_f32_32x32x16_bf16 v[16:31], v[6:9], v[10:13], v[16:31]
	v_or_b32_e32 v6, 0xe0, v136
	v_bitop3_b32 v161, v6, v14, v225 bitop3:0xde
	v_lshlrev_b32_e32 v14, 7, v148
	v_bitop3_b32 v86, v136, v14, v85 bitop3:0xde
	v_or_b32_e32 v169, 0x10000, v86
	v_or_b32_e32 v170, 0x11000, v86
	v_bitop3_b32 v87, v15, v14, v85 bitop3:0xde
	s_waitcnt lgkmcnt(1)
	v_mfma_f32_32x32x16_bf16 v[32:47], v[52:55], v[10:13], v[32:47]
	ds_read_b128 v[6:9], v161 offset:32768
	ds_read_b128 v[10:13], v161 offset:40960
	v_or_b32_e32 v171, 0x10000, v87
	v_or_b32_e32 v172, 0x11000, v87
	v_bitop3_b32 v88, v78, v14, v85 bitop3:0xde
	v_or_b32_e32 v173, 0x10000, v88
	v_bitop3_b32 v175, v79, v14, v85 bitop3:0xde
	v_or_b32_e32 v174, 0x11000, v88
	s_waitcnt lgkmcnt(1)
	v_mfma_f32_32x32x16_bf16 v[16:31], v[6:9], v[56:59], v[16:31]
	v_or_b32_e32 v176, 0x10000, v175
	v_or_b32_e32 v178, 0x11000, v175
	v_or_b32_e32 v184, 0x12000, v86
	v_or_b32_e32 v185, 0x13000, v86
	v_or_b32_e32 v181, 0x12000, v87
	v_or_b32_e32 v182, 0x13000, v87
	v_or_b32_e32 v179, 0x12000, v88
	s_waitcnt lgkmcnt(0)
	v_mfma_f32_32x32x16_bf16 v[32:47], v[10:13], v[56:59], v[32:47]
	ds_read_b128 v[6:9], v169
	ds_read_b128 v[10:13], v77 offset:4096
	ds_read_b128 v[52:55], v170
	ds_read_b128 v[56:59], v77 offset:5120
	v_or_b32_e32 v180, 0x13000, v88
	s_waitcnt lgkmcnt(2)
	v_mfma_f32_32x32x16_bf16 v[16:31], v[6:9], v[10:13], v[16:31]
	ds_read_b128 v[6:9], v171
	s_waitcnt lgkmcnt(2)
	v_mfma_f32_32x32x16_bf16 v[32:47], v[52:55], v[10:13], v[32:47]
	v_lshl_add_u64 v[10:11], v[2:3], 0, s[4:5]
	s_mov_b64 s[4:5], 0xc0000
	v_lshl_add_u64 v[12:13], v[2:3], 0, s[4:5]
	global_load_dwordx4 v[52:55], v[10:11], off offset:256
	global_load_dwordx4 v[60:63], v[12:13], off offset:256
	v_add_co_u32_e32 v10, vcc, s73, v2
	v_mad_i64_i32 v[80:81], s[4:5], v76, s71, 0
	s_nop 0
	v_addc_co_u32_e32 v11, vcc, 0, v3, vcc
	v_add_co_u32_e32 v2, vcc, s74, v2
	s_waitcnt lgkmcnt(0)
	v_mfma_f32_32x32x16_bf16 v[16:31], v[6:9], v[56:59], v[16:31]
	v_addc_co_u32_e32 v3, vcc, 0, v3, vcc
	global_load_dwordx4 v[64:67], v[10:11], off
	global_load_dwordx4 v[68:71], v[2:3], off
	v_add_u32_e32 v2, 64, v76
	v_mad_i64_i32 v[2:3], s[4:5], v2, s71, v[4:5]
	v_lshl_add_u64 v[0:1], v[2:3], 0, v[0:1]
	global_load_dwordx4 v[72:75], v[0:1], off offset:2048
	v_lshlrev_b32_e32 v4, 3, v82
	v_and_b32_e32 v0, 0xc0, v83
	v_and_or_b32 v5, v4, 24, v0
	ds_read_b128 v[0:3], v172
	v_lshlrev_b32_e32 v6, 1, v50
	v_and_b32_e32 v6, 32, v6
	v_and_b32_e32 v4, 0x100, v4
	v_or3_b32 v153, v5, v6, v4
	ds_read_b128 v[4:7], v173
	s_waitcnt lgkmcnt(1)
	v_mfma_f32_32x32x16_bf16 v[32:47], v[0:3], v[56:59], v[32:47]
	ds_read_b128 v[0:3], v77 offset:6144
	ds_read_b128 v[8:11], v174
	ds_read_b128 v[56:59], v77 offset:7168
	ds_read_b128 v[76:79], v178
	s_mov_b32 s4, s29
	s_mov_b32 s5, s29
	v_or_b32_e32 v152, 0x4000, v153
	s_waitcnt lgkmcnt(3)
	v_mfma_f32_32x32x16_bf16 v[16:31], v[4:7], v[0:3], v[16:31]
	ds_read_b128 v[4:7], v176
	s_waitcnt vmcnt(0)
	s_waitcnt vmcnt(4)
	ds_write_b128 v154, v[52:55] offset:16384
	s_waitcnt vmcnt(3)
	ds_write_b128 v155, v[60:63] offset:16384
	v_mov_b32_e32 v238, v52
	v_mov_b32_e32 v239, v53
	v_mov_b32_e32 v240, v54
	v_mov_b32_e32 v241, v55
	v_mov_b32_e32 v242, v60
	v_mov_b32_e32 v243, v61
	v_mov_b32_e32 v244, v62
	v_mov_b32_e32 v245, v63
	s_waitcnt vmcnt(2)
	ds_write_b128 v156, v[64:67] offset:49152
	s_waitcnt vmcnt(1)
	ds_write_b128 v157, v[68:71] offset:49152
	s_waitcnt lgkmcnt(7)
	v_mfma_f32_32x32x16_bf16 v[32:47], v[8:11], v[0:3], v[32:47]
	s_waitcnt vmcnt(0)
	ds_write_b128 v183, v[72:75]
	s_waitcnt lgkmcnt(0)
	s_barrier
; DEV void partialSM(f32x16& p0, f32x16& p1, float& m_reg, float& mn, float& alpha) {
;   constexpr float C = SCALE * 1.4426950408889634f;
;   float pmax = p0[0];
; #pragma unroll
;   for (int r = 1; r < 16; ++r) pmax = fmaxf(pmax, p0[r]);
; #pragma unroll
;   for (int r = 0; r < 16; ++r) pmax = fmaxf(pmax, p1[r]);
;   { auto rr = __builtin_amdgcn_permlane32_swap(__float_as_uint(pmax), __float_as_uint(pmax), false, false);
;     pmax = fmaxf(__uint_as_float(rr[0]), __uint_as_float(rr[1])); }
;   if (__builtin_expect(__all(pmax - m_reg <= THR / SCALE), 1)) { mn = m_reg; alpha = 1.f; }
;   else { mn = fmaxf(m_reg, pmax); alpha = __builtin_amdgcn_exp2f((m_reg - mn) * C); m_reg = mn; }
;   float mnC = -mn * C;
; #pragma unroll
;   for (int r = 0; r < 16; ++r) p0[r] = fmaf(p0[r], C, mnC);
; #pragma unroll
;   for (int r = 0; r < 16; ++r) p1[r] = fmaf(p1[r], C, mnC);
; #pragma unroll
;   for (int r = 0; r < 16; ++r) p0[r] = __builtin_amdgcn_exp2f(p0[r]);
; }
	v_mfma_f32_32x32x16_bf16 v[16:31], v[4:7], v[56:59], v[16:31]
	v_mov_b64_e32 v[0:1], s[4:5]
	v_mov_b64_e32 v[2:3], s[6:7]
	v_mov_b64_e32 v[4:5], s[8:9]
	v_mov_b64_e32 v[6:7], s[10:11]
	v_mov_b64_e32 v[8:9], s[12:13]
	v_mov_b64_e32 v[10:11], s[14:15]
	v_mov_b64_e32 v[12:13], s[16:17]
	v_mfma_f32_32x32x16_bf16 v[32:47], v[76:79], v[56:59], v[32:47]
	s_nop 3
	v_max_f32_e32 v56, v17, v17
	v_max_f32_e32 v57, v16, v16
	v_max_f32_e32 v56, v57, v56
	v_max3_f32 v56, v56, v18, v19
	v_max3_f32 v56, v56, v20, v21
	v_max3_f32 v56, v56, v22, v23
	v_max3_f32 v56, v56, v24, v25
	v_max3_f32 v56, v56, v26, v27
	v_max3_f32 v56, v56, v28, v29
	v_max3_f32 v56, v56, v30, v31
	v_max3_f32 v56, v56, v32, v33
	v_max3_f32 v56, v56, v34, v35
	v_max3_f32 v56, v56, v36, v37
	v_max3_f32 v56, v56, v38, v39
	v_max3_f32 v56, v56, v40, v41
	v_max3_f32 v56, v56, v42, v43
	v_max3_f32 v56, v56, v44, v45
	v_max3_f32 v56, v56, v46, v47
	v_mov_b32_e32 v57, v56
	s_nop 1
	v_permlane32_swap_b32_e32 v56, v57
	v_max_f32_e32 v57, v57, v57
	v_max_f32_e32 v56, v56, v56
	v_max_f32_e32 v56, v56, v57
	v_add_f32_e32 v57, 0x7149f2ca, v56
	v_cmp_ge_f32_e32 vcc, s72, v57
	s_cmp_eq_u64 vcc, exec
	v_max_f32_e32 v53, 0xf149f2ca, v56
	s_cselect_b64 vcc, -1, 0
	v_cndmask_b32_e32 v132, v53, v146, vcc
	v_mul_f32_e32 v52, 0xbdd53b94, v132
	v_fmamk_f32 v16, v16, 0x3dd53b94, v52
	v_exp_f32_e32 v196, v16
	v_fmamk_f32 v16, v17, 0x3dd53b94, v52
	v_exp_f32_e32 v199, v16
	v_fmamk_f32 v16, v18, 0x3dd53b94, v52
	v_exp_f32_e32 v197, v16
	v_fmamk_f32 v16, v19, 0x3dd53b94, v52
	v_exp_f32_e32 v200, v16
	v_fmamk_f32 v16, v20, 0x3dd53b94, v52
	v_exp_f32_e32 v198, v16
	v_fmamk_f32 v16, v21, 0x3dd53b94, v52
	v_exp_f32_e32 v201, v16
	v_fmamk_f32 v16, v22, 0x3dd53b94, v52
	v_exp_f32_e32 v194, v16
	v_fmamk_f32 v16, v23, 0x3dd53b94, v52
	v_exp_f32_e32 v195, v16
	v_fmamk_f32 v16, v24, 0x3dd53b94, v52
	v_exp_f32_e32 v134, v16
	v_fmamk_f32 v16, v25, 0x3dd53b94, v52
	v_exp_f32_e32 v192, v16
	v_fmamk_f32 v16, v26, 0x3dd53b94, v52
	v_exp_f32_e32 v135, v16
	v_fmamk_f32 v16, v27, 0x3dd53b94, v52
	v_exp_f32_e32 v193, v16
	v_fmamk_f32 v16, v28, 0x3dd53b94, v52
	v_exp_f32_e32 v128, v16
	v_fmamk_f32 v16, v29, 0x3dd53b94, v52
	v_pk_fma_f32 v[116:117], v[38:39], s[30:31], v[52:53] op_sel_hi:[1,0,0]
	v_sub_f32_e32 v38, 0xf149f2ca, v53
	v_exp_f32_e32 v130, v16
	v_fmamk_f32 v16, v30, 0x3dd53b94, v52
	v_mov_b64_e32 v[14:15], s[18:19]
	v_mul_f32_e32 v38, 0x3dd53b94, v38
	v_exp_f32_e32 v129, v16
	v_mad_u64_u32 v[16:17], s[4:5], s54, v147, v[80:81]
	v_and_b32_e32 v18, 7, v50
	v_exp_f32_e32 v38, v38
	v_add_u32_e32 v17, s0, v17
	v_lshl_or_b32 v16, v18, 4, v16
	v_pk_fma_f32 v[114:115], v[46:47], s[30:31], v[52:53] op_sel_hi:[1,0,0]
	v_pk_fma_f32 v[118:119], v[44:45], s[30:31], v[52:53] op_sel_hi:[1,0,0]
	v_pk_fma_f32 v[122:123], v[42:43], s[30:31], v[52:53] op_sel_hi:[1,0,0]
	v_pk_fma_f32 v[112:113], v[40:41], s[30:31], v[52:53] op_sel_hi:[1,0,0]
	v_pk_fma_f32 v[120:121], v[36:37], s[30:31], v[52:53] op_sel_hi:[1,0,0]
	v_pk_fma_f32 v[124:125], v[34:35], s[30:31], v[52:53] op_sel_hi:[1,0,0]
	v_pk_fma_f32 v[126:127], v[32:33], s[30:31], v[52:53] op_sel_hi:[1,0,0]
	v_fmac_f32_e32 v52, 0x3dd53b94, v31
	v_lshl_add_u64 v[140:141], s[26:27], 0, v[16:17]
	v_lshl_add_u64 v[16:17], s[54:55], 0, v[48:49]
	v_exp_f32_e32 v131, v52
	v_lshlrev_b64 v[16:17], 13, v[16:17]
	v_and_b32_e32 v18, 15, v50
	s_add_u32 s0, s31, s62
	v_lshl_or_b32 v16, v18, 4, v16
	s_addc_u32 s1, s70, s63
	v_cndmask_b32_e64 v186, v38, 1.0, vcc
	v_lshl_add_u64 v[142:143], s[0:1], 0, v[16:17]
	v_mov_b64_e32 v[62:63], v[14:15]
	v_mov_b64_e32 v[46:47], v[14:15]
	v_mov_b64_e32 v[30:31], v[14:15]
	v_cmp_gt_u32_e64 s[6:7], 32, v82
	v_mov_b64_e32 v[60:61], v[12:13]
	v_mov_b64_e32 v[58:59], v[10:11]
	v_mov_b64_e32 v[56:57], v[8:9]
	v_mov_b64_e32 v[54:55], v[6:7]
	v_mov_b64_e32 v[52:53], v[4:5]
	v_mov_b64_e32 v[50:51], v[2:3]
	v_mov_b64_e32 v[48:49], v[0:1]
	v_mov_b64_e32 v[44:45], v[12:13]
	v_mov_b64_e32 v[42:43], v[10:11]
	v_mov_b64_e32 v[40:41], v[8:9]
	v_mov_b64_e32 v[38:39], v[6:7]
	v_mov_b64_e32 v[36:37], v[4:5]
	v_mov_b64_e32 v[34:35], v[2:3]
	v_mov_b64_e32 v[32:33], v[0:1]
	v_mov_b64_e32 v[28:29], v[12:13]
	v_mov_b64_e32 v[26:27], v[10:11]
	v_mov_b64_e32 v[24:25], v[8:9]
	v_mov_b64_e32 v[22:23], v[6:7]
	v_mov_b64_e32 v[20:21], v[4:5]
	v_mov_b64_e32 v[18:19], v[2:3]
	v_mov_b64_e32 v[16:17], v[0:1]
; #define SBAR() __builtin_amdgcn_sched_barrier(0)
; #define SLOAD(i, k0) do { sr_[i].vs0 = LD8(&Vh[(long)((k0) + sr) * LDK + sc]); sr_[i].vs1 = LD8(&Vh[(long)((k0) + 32 + sr) * LDK + sc]); \
;     sr_[i].ks0 = LD8(&Kh[(long)((k0) + sr) * LDK + sc]); sr_[i].ks1 = LD8(&Kh[(long)((k0) + 32 + sr) * LDK + sc]); \
;     sr_[i].kp = LD8(&KPh[(long)((k0) + pr) * LDKP + pc]); } while (0)
; DEV void qkt(f32x16& p0, f32x16& p1, const char* Ks, const char* KPs, const bf16x8* qr, const char* qpl, int r32, int hi) {
;   p0 = f32x16{}; p1 = f32x16{};
; #pragma unroll
;   for (int d0 = 0; d0 < 8; ++d0) { int cb = (d0 * 16 + hi * 8) * 2;
;     bf16x8 b0 = *reinterpret_cast<const bf16x8*>(Ks + KSWZ(r32, cb));
;     bf16x8 b1 = *reinterpret_cast<const bf16x8*>(Ks + KSWZ(32 + r32, cb));
;     bf16x8 qq = d0 < NQR ? qr[d0 < NQR ? d0 : 0] : *reinterpret_cast<const bf16x8*>(qpl + (d0 - NQR) * 1024);
;     p0 = __builtin_amdgcn_mfma_f32_32x32x16_bf16(b0, qq, p0, 0, 0, 0);
;     p1 = __builtin_amdgcn_mfma_f32_32x32x16_bf16(b1, qq, p1, 0, 0, 0); }
; #pragma unroll
;   for (int d1 = 0; d1 < 4; ++d1) { int cb = (d1 * 16 + hi * 8) * 2;
;     bf16x8 b0 = *reinterpret_cast<const bf16x8*>(KPs + KPSWZ(r32, cb));
;     bf16x8 b1 = *reinterpret_cast<const bf16x8*>(KPs + KPSWZ(32 + r32, cb));
;     bf16x8 qp = *reinterpret_cast<const bf16x8*>(qpl + (8 - NQR + d1) * 1024);
;     p0 = __builtin_amdgcn_mfma_f32_32x32x16_bf16(b0, qp, p0, 0, 0, 0);
;     p1 = __builtin_amdgcn_mfma_f32_32x32x16_bf16(b1, qp, p1, 0, 0, 0); }
; }
; DEV void attn_item(const u16* __restrict__ Qb, const u16* __restrict__ Kh, const u16* __restrict__ Vh, const u16* __restrict__ KPh,
;                    u16* __restrict__ Ob, int seq, char* lds) {
;     ...
;   for (int j = 1; j + 1 < NT; j += 2) {
;     SBAR(); qkt(pB0, pB1, K_lds + SHM_K, KP_lds + SHM_KP, qr, qpl, r32, hi);
;     finishSM(pA0, pA1, alA, l_reg, pa0, pa1, pa2, pa3); SBAR();
;     SLOAD(SO, (j + 1) * KVBLK); SBAR();
.LBB0_304:
	s_waitcnt vmcnt(0)
	ds_write_b128 v154, v[238:241] offset:16384
	ds_write_b128 v155, v[242:245] offset:16384
	s_mov_b32 s0, 0x40000
	v_add_co_u32_e32 v224, vcc, s0, v142
	s_nop 1
	v_addc_co_u32_e32 v225, vcc, 0, v143, vcc
	global_load_dwordx4 v[226:229], v[142:143], off
	global_load_dwordx4 v[230:233], v[224:225], off
	global_load_dwordx4 v[234:237], v[140:141], off
	global_load_dwordx4 v[238:241], v[142:143], off offset:256
	global_load_dwordx4 v[242:245], v[224:225], off offset:256
	ds_read_b128 v[64:67], v159 offset:49152
	ds_read_b128 v[68:71], v159 offset:57344
	ds_read_b128 v[188:191], v162 offset:49152
	ds_read_b128 v[202:205], v162 offset:57344
	v_add_f32_e32 v133, 0, v196
	v_add_f32_e32 v133, v199, v133
	s_waitcnt lgkmcnt(3)
	v_mfma_f32_32x32x16_bf16 v[80:95], v[64:67], v[108:111], 0
	v_add_f32_e32 v133, v197, v133
	v_add_f32_e32 v133, v200, v133
	v_add_f32_e32 v133, v198, v133
	v_add_f32_e32 v133, v201, v133
	v_add_f32_e32 v133, v194, v133
	v_add_f32_e32 v133, v195, v133
	v_add_f32_e32 v133, v134, v133
	s_waitcnt lgkmcnt(2)
	v_mfma_f32_32x32x16_bf16 v[64:79], v[68:71], v[108:111], 0
	v_add_f32_e32 v133, v192, v133
	v_add_f32_e32 v133, v135, v133
	v_add_f32_e32 v133, v193, v133
	v_exp_f32_e32 v126, v126
	v_add_f32_e32 v133, v128, v133
	v_exp_f32_e32 v127, v127
	v_add_f32_e32 v133, v130, v133
	s_waitcnt lgkmcnt(0)
	v_mfma_f32_32x32x16_bf16 v[64:79], v[202:205], v[104:107], v[64:79]
	v_exp_f32_e32 v124, v124
	v_add_f32_e32 v133, v129, v133
	v_exp_f32_e32 v125, v125
	v_add_f32_e32 v133, v131, v133
	v_or_b32_e32 v187, 0x12000, v175
	v_exp_f32_e32 v120, v120
	v_add_f32_e32 v133, v126, v133
	v_mfma_f32_32x32x16_bf16 v[80:95], v[188:191], v[104:107], v[80:95]
	ds_read_b128 v[188:191], v163 offset:49152
	ds_read_b128 v[202:205], v163 offset:57344
	v_exp_f32_e32 v121, v121
	v_add_f32_e32 v133, v127, v133
	v_exp_f32_e32 v116, v116
	v_add_f32_e32 v133, v124, v133
	v_exp_f32_e32 v117, v117
	v_add_f32_e32 v133, v125, v133
	s_waitcnt lgkmcnt(0)
	v_mfma_f32_32x32x16_bf16 v[64:79], v[202:205], v[100:103], v[64:79]
	v_exp_f32_e32 v112, v112
	v_add_f32_e32 v133, v120, v133
	v_exp_f32_e32 v113, v113
	v_add_f32_e32 v133, v121, v133
	v_exp_f32_e32 v122, v122
	v_add_f32_e32 v133, v116, v133
	v_exp_f32_e32 v123, v123
	v_mfma_f32_32x32x16_bf16 v[80:95], v[188:191], v[100:103], v[80:95]
	ds_read_b128 v[188:191], v166 offset:49152
	ds_read_b128 v[202:205], v166 offset:57344
	v_add_f32_e32 v133, v117, v133
	v_exp_f32_e32 v118, v118
	v_add_f32_e32 v133, v112, v133
	v_exp_f32_e32 v119, v119
	v_add_f32_e32 v133, v113, v133
	v_exp_f32_e32 v114, v114
	s_waitcnt lgkmcnt(0)
	v_mfma_f32_32x32x16_bf16 v[64:79], v[202:205], v[96:99], v[64:79]
	v_add_f32_e32 v133, v122, v133
	v_exp_f32_e32 v115, v115
	v_add_f32_e32 v133, v123, v133
	v_add_f32_e32 v133, v118, v133
	v_add_f32_e32 v133, v119, v133
	v_add_f32_e32 v133, v114, v133
	v_mfma_f32_32x32x16_bf16 v[80:95], v[188:191], v[96:99], v[80:95]
	ds_read_b128 v[188:191], v167 offset:49152
	ds_read_b128 v[202:205], v167 offset:57344
	ds_read_b128 v[206:209], v177
	s_waitcnt lgkmcnt(0)
	v_mfma_f32_32x32x16_bf16 v[64:79], v[202:205], v[206:209], v[64:79]
	v_mfma_f32_32x32x16_bf16 v[80:95], v[188:191], v[206:209], v[80:95]
	ds_read_b128 v[188:191], v168 offset:49152
	ds_read_b128 v[202:205], v168 offset:57344
	ds_read_b128 v[206:209], v177 offset:1024
	s_waitcnt lgkmcnt(0)
	v_mfma_f32_32x32x16_bf16 v[64:79], v[202:205], v[206:209], v[64:79]
	v_mfma_f32_32x32x16_bf16 v[80:95], v[188:191], v[206:209], v[80:95]
	ds_read_b128 v[188:191], v160 offset:49152
	ds_read_b128 v[202:205], v160 offset:57344
	ds_read_b128 v[206:209], v177 offset:2048
	s_waitcnt lgkmcnt(0)
	v_mfma_f32_32x32x16_bf16 v[64:79], v[202:205], v[206:209], v[64:79]
	v_mfma_f32_32x32x16_bf16 v[80:95], v[188:191], v[206:209], v[80:95]
	ds_read_b128 v[188:191], v161 offset:49152
	ds_read_b128 v[202:205], v161 offset:57344
	ds_read_b128 v[206:209], v177 offset:3072
	s_waitcnt lgkmcnt(0)
	v_mfma_f32_32x32x16_bf16 v[64:79], v[202:205], v[206:209], v[64:79]
	v_mfma_f32_32x32x16_bf16 v[80:95], v[188:191], v[206:209], v[80:95]
	ds_read_b128 v[188:191], v184
	ds_read_b128 v[202:205], v185
	ds_read_b128 v[206:209], v177 offset:4096
	s_waitcnt lgkmcnt(0)
	v_mfma_f32_32x32x16_bf16 v[64:79], v[202:205], v[206:209], v[64:79]
	v_mfma_f32_32x32x16_bf16 v[80:95], v[188:191], v[206:209], v[80:95]
	ds_read_b128 v[188:191], v181
	ds_read_b128 v[202:205], v182
	ds_read_b128 v[206:209], v177 offset:5120
	s_waitcnt lgkmcnt(0)
	v_mfma_f32_32x32x16_bf16 v[64:79], v[202:205], v[206:209], v[64:79]
	v_mfma_f32_32x32x16_bf16 v[80:95], v[188:191], v[206:209], v[80:95]
	ds_read_b128 v[188:191], v179
	ds_read_b128 v[202:205], v180
	ds_read_b128 v[206:209], v177 offset:6144
	s_waitcnt lgkmcnt(0)
	v_mfma_f32_32x32x16_bf16 v[64:79], v[202:205], v[206:209], v[64:79]
	ds_read_b128 v[202:205], v187
	v_mfma_f32_32x32x16_bf16 v[80:95], v[188:191], v[206:209], v[80:95]
	v_or_b32_e32 v188, 0x13000, v175
	ds_read_b128 v[206:209], v188
	ds_read_b128 v[210:213], v177 offset:7168
	v_add_f32_e32 v189, v115, v133
	v_mov_b32_e32 v190, v189
	s_nop 1
	v_permlane32_swap_b32_e32 v189, v190
	v_cvt_pk_bf16_f32 v196, v196, v199
	s_waitcnt lgkmcnt(0)
; #define SBAR() __builtin_amdgcn_sched_barrier(0)
; #define SLOAD(i, k0) do { sr_[i].vs0 = LD8(&Vh[(long)((k0) + sr) * LDK + sc]); sr_[i].vs1 = LD8(&Vh[(long)((k0) + 32 + sr) * LDK + sc]); \
;     sr_[i].ks0 = LD8(&Kh[(long)((k0) + sr) * LDK + sc]); sr_[i].ks1 = LD8(&Kh[(long)((k0) + 32 + sr) * LDK + sc]); \
;     sr_[i].kp = LD8(&KPh[(long)((k0) + pr) * LDKP + pc]); } while (0)
; #define SWAIT() asm volatile("s_waitcnt vmcnt(0)" ::: "memory")
; #define RESC(a) do { if (__any((a) < 1.f)) { if (hi == 0) al_l[r32] = (a); asm volatile("s_waitcnt lgkmcnt(0)" ::: "memory"); \
;     _Pragma("unroll") for (int d = 0; d < 4; ++d) _Pragma("unroll") for (int r = 0; r < 16; ++r) o[d][r] *= al_l[crow(r, hi)]; } } while (0)
; DEV void partialSM(f32x16& p0, f32x16& p1, float& m_reg, float& mn, float& alpha) {
;   constexpr float C = SCALE * 1.4426950408889634f;
;   float pmax = p0[0];
; #pragma unroll
;   for (int r = 1; r < 16; ++r) pmax = fmaxf(pmax, p0[r]);
; #pragma unroll
;   for (int r = 0; r < 16; ++r) pmax = fmaxf(pmax, p1[r]);
;   { auto rr = __builtin_amdgcn_permlane32_swap(__float_as_uint(pmax), __float_as_uint(pmax), false, false);
;     pmax = fmaxf(__uint_as_float(rr[0]), __uint_as_float(rr[1])); }
;   if (__builtin_expect(__all(pmax - m_reg <= THR / SCALE), 1)) { mn = m_reg; alpha = 1.f; }
;   else { mn = fmaxf(m_reg, pmax); alpha = __builtin_amdgcn_exp2f((m_reg - mn) * C); m_reg = mn; }
;   float mnC = -mn * C;
; #pragma unroll
;   for (int r = 0; r < 16; ++r) p0[r] = fmaf(p0[r], C, mnC);
; #pragma unroll
;   for (int r = 0; r < 16; ++r) p1[r] = fmaf(p1[r], C, mnC);
; #pragma unroll
;   for (int r = 0; r < 16; ++r) p0[r] = __builtin_amdgcn_exp2f(p0[r]);
; }
; DEV void attn_item(const u16* __restrict__ Qb, const u16* __restrict__ Kh, const u16* __restrict__ Vh, const u16* __restrict__ KPh,
;                    u16* __restrict__ Ob, int seq, char* lds) {
;     ...
;     finishSM(pA0, pA1, alA, l_reg, pa0, pa1, pa2, pa3); SBAR();
;     SLOAD(SO, (j + 1) * KVBLK); SBAR();
;     pv_d0(o, vb0, pa0, pa1, pa2, pa3); partialSM(pB0, pB1, m_reg, mnB, alB);
;     __syncthreads(); SWAIT(); SWRITE(0, SE);
;     RESC(alB); __syncthreads();
	v_mfma_f32_32x32x16_bf16 v[80:95], v[202:205], v[210:213], v[80:95]
	v_cvt_pk_bf16_f32 v197, v197, v200
	v_cvt_pk_bf16_f32 v198, v198, v201
	v_cvt_pk_bf16_f32 v199, v194, v195
	v_cvt_pk_bf16_f32 v192, v134, v192
	v_cvt_pk_bf16_f32 v193, v135, v193
	v_cvt_pk_bf16_f32 v194, v128, v130
	v_cvt_pk_bf16_f32 v195, v129, v131
	v_mfma_f32_32x32x16_bf16 v[64:79], v[206:209], v[210:213], v[64:79]
	v_cvt_pk_bf16_f32 v200, v126, v127
	v_cvt_pk_bf16_f32 v201, v124, v125
	v_cvt_pk_bf16_f32 v202, v120, v121
	v_cvt_pk_bf16_f32 v203, v116, v117
	v_cvt_pk_bf16_f32 v204, v112, v113
	v_cvt_pk_bf16_f32 v205, v122, v123
	v_cvt_pk_bf16_f32 v206, v118, v119
	v_cvt_pk_bf16_f32 v207, v114, v115
	v_permlane32_swap_b32_e32 v196, v198
	v_permlane32_swap_b32_e32 v197, v199
	v_permlane32_swap_b32_e32 v192, v194
	v_permlane32_swap_b32_e32 v193, v195
	v_permlane32_swap_b32_e32 v200, v202
	v_permlane32_swap_b32_e32 v201, v203
	v_permlane32_swap_b32_e32 v204, v206
	v_permlane32_swap_b32_e32 v205, v207
	s_waitcnt vmcnt(2)
	ds_write_b128 v156, v[226:229] offset:32768
	ds_write_b128 v157, v[230:233] offset:32768
	ds_write_b128 v158, v[234:237]
	ds_read_b64_tr_b16 v[208:209], v153 offset:0
	ds_read_b64_tr_b16 v[210:211], v153 offset:0x800
	ds_read_b64_tr_b16 v[212:213], v153 offset:0x1000
	ds_read_b64_tr_b16 v[214:215], v153 offset:0x1800
	ds_read_b64_tr_b16 v[216:217], v153 offset:0x2000
	ds_read_b64_tr_b16 v[218:219], v153 offset:0x2800
	ds_read_b64_tr_b16 v[220:221], v153 offset:0x3000
	ds_read_b64_tr_b16 v[222:223], v153 offset:0x3800
	s_waitcnt lgkmcnt(6)
	s_nop 0
	v_mfma_f32_32x32x16_bf16 v[0:15], v[196:199], v[208:211], v[0:15]
	ds_read_b64_tr_b16 v[208:209], v153 offset:0x200
	ds_read_b64_tr_b16 v[210:211], v153 offset:0xa00
	v_max_f32_e32 v133, v81, v81
	v_max_f32_e32 v134, v80, v80
	v_max_f32_e32 v133, v134, v133
	v_max3_f32 v133, v133, v82, v83
	v_max3_f32 v133, v133, v84, v85
	s_waitcnt lgkmcnt(6)
	v_mfma_f32_32x32x16_bf16 v[0:15], v[192:195], v[212:215], v[0:15]
	ds_read_b64_tr_b16 v[212:213], v153 offset:0x1200
	ds_read_b64_tr_b16 v[214:215], v153 offset:0x1a00
	v_max3_f32 v133, v133, v86, v87
	v_max3_f32 v133, v133, v88, v89
	v_max3_f32 v133, v133, v90, v91
	v_max3_f32 v133, v133, v92, v93
	v_max3_f32 v133, v133, v94, v95
	s_waitcnt lgkmcnt(6)
	v_mfma_f32_32x32x16_bf16 v[0:15], v[200:203], v[216:219], v[0:15]
	ds_read_b64_tr_b16 v[216:217], v153 offset:0x2200
	ds_read_b64_tr_b16 v[218:219], v153 offset:0x2a00
	v_max3_f32 v133, v133, v64, v65
	v_max3_f32 v133, v133, v66, v67
	v_max3_f32 v133, v133, v68, v69
	v_max3_f32 v133, v133, v70, v71
	v_max3_f32 v133, v133, v72, v73
	s_waitcnt lgkmcnt(6)
	v_mfma_f32_32x32x16_bf16 v[0:15], v[204:207], v[220:223], v[0:15]
	ds_read_b64_tr_b16 v[220:221], v153 offset:0x3200
	ds_read_b64_tr_b16 v[222:223], v153 offset:0x3a00
	v_max3_f32 v133, v133, v74, v75
	v_max3_f32 v133, v133, v76, v77
	v_max3_f32 v133, v133, v78, v79
	v_mov_b32_e32 v134, v133
	s_waitcnt lgkmcnt(6)
	v_mfma_f32_32x32x16_bf16 v[48:63], v[196:199], v[208:211], v[48:63]
	ds_read_b64_tr_b16 v[208:209], v153 offset:0x400
	ds_read_b64_tr_b16 v[210:211], v153 offset:0xc00
	s_nop 1
	v_permlane32_swap_b32_e32 v133, v134
	v_max_f32_e32 v134, v134, v134
	v_max_f32_e32 v133, v133, v133
	s_waitcnt lgkmcnt(6)
	v_mfma_f32_32x32x16_bf16 v[48:63], v[192:195], v[212:215], v[48:63]
	ds_read_b64_tr_b16 v[212:213], v153 offset:0x1400
	ds_read_b64_tr_b16 v[214:215], v153 offset:0x1c00
	v_max_f32_e32 v133, v133, v134
	v_sub_f32_e32 v134, v133, v132
	v_cmp_ge_f32_e32 vcc, s72, v134
	v_max_f32_e32 v134, v132, v132
	s_waitcnt lgkmcnt(6)
	v_mfma_f32_32x32x16_bf16 v[48:63], v[200:203], v[216:219], v[48:63]
	ds_read_b64_tr_b16 v[216:217], v153 offset:0x2400
	ds_read_b64_tr_b16 v[218:219], v153 offset:0x2c00
	v_max_f32_e32 v133, v134, v133
	v_sub_f32_e32 v134, v132, v133
	v_mul_f32_e32 v134, 0x3dd53b94, v134
	v_exp_f32_e32 v134, v134
	s_waitcnt lgkmcnt(6)
	v_mfma_f32_32x32x16_bf16 v[48:63], v[204:207], v[220:223], v[48:63]
	ds_read_b64_tr_b16 v[220:221], v153 offset:0x3400
	ds_read_b64_tr_b16 v[222:223], v153 offset:0x3c00
	s_cmp_eq_u64 vcc, exec
	s_cselect_b64 s[4:5], -1, 0
	v_cndmask_b32_e64 v226, v133, v132, s[4:5]
	v_mul_f32_e32 v227, 0xbdd53b94, v226
	s_waitcnt lgkmcnt(6)
	v_mfma_f32_32x32x16_bf16 v[32:47], v[196:199], v[208:211], v[32:47]
	ds_read_b64_tr_b16 v[208:209], v153 offset:0x600
	ds_read_b64_tr_b16 v[210:211], v153 offset:0xe00
	v_fmamk_f32 v80, v80, 0x3dd53b94, v227
	v_fmamk_f32 v81, v81, 0x3dd53b94, v227
	v_fmamk_f32 v82, v82, 0x3dd53b94, v227
	v_fmamk_f32 v83, v83, 0x3dd53b94, v227
	s_waitcnt lgkmcnt(6)
	v_mfma_f32_32x32x16_bf16 v[32:47], v[192:195], v[212:215], v[32:47]
	ds_read_b64_tr_b16 v[212:213], v153 offset:0x1600
	ds_read_b64_tr_b16 v[214:215], v153 offset:0x1e00
	v_fmamk_f32 v84, v84, 0x3dd53b94, v227
	v_fmamk_f32 v85, v85, 0x3dd53b94, v227
	v_fmamk_f32 v86, v86, 0x3dd53b94, v227
	v_fmamk_f32 v87, v87, 0x3dd53b94, v227
	s_waitcnt lgkmcnt(6)
	v_mfma_f32_32x32x16_bf16 v[32:47], v[200:203], v[216:219], v[32:47]
	ds_read_b64_tr_b16 v[216:217], v153 offset:0x2600
	ds_read_b64_tr_b16 v[218:219], v153 offset:0x2e00
	v_fmamk_f32 v88, v88, 0x3dd53b94, v227
	v_fmamk_f32 v89, v89, 0x3dd53b94, v227
	v_fmamk_f32 v90, v90, 0x3dd53b94, v227
	v_fmamk_f32 v91, v91, 0x3dd53b94, v227
	s_waitcnt lgkmcnt(6)
	v_mfma_f32_32x32x16_bf16 v[32:47], v[204:207], v[220:223], v[32:47]
	ds_read_b64_tr_b16 v[220:221], v153 offset:0x3600
	ds_read_b64_tr_b16 v[222:223], v153 offset:0x3e00
	v_fmamk_f32 v92, v92, 0x3dd53b94, v227
	v_fmamk_f32 v93, v93, 0x3dd53b94, v227
	v_fmamk_f32 v94, v94, 0x3dd53b94, v227
	v_fmamk_f32 v95, v95, 0x3dd53b94, v227
	s_waitcnt lgkmcnt(6)
	v_mfma_f32_32x32x16_bf16 v[16:31], v[196:199], v[208:211], v[16:31]
	v_exp_f32_e32 v125, v80
	v_exp_f32_e32 v127, v81
	v_exp_f32_e32 v123, v82
	v_exp_f32_e32 v126, v83
	s_waitcnt lgkmcnt(4)
	v_mfma_f32_32x32x16_bf16 v[16:31], v[192:195], v[212:215], v[16:31]
	v_exp_f32_e32 v122, v84
	v_exp_f32_e32 v124, v85
	v_exp_f32_e32 v120, v86
	v_exp_f32_e32 v121, v87
	s_waitcnt lgkmcnt(2)
	v_mfma_f32_32x32x16_bf16 v[16:31], v[200:203], v[216:219], v[16:31]
	v_exp_f32_e32 v117, v88
	v_exp_f32_e32 v119, v89
	v_exp_f32_e32 v116, v90
	v_exp_f32_e32 v118, v91
	s_waitcnt lgkmcnt(0)
	v_mfma_f32_32x32x16_bf16 v[16:31], v[204:207], v[220:223], v[16:31]
	v_exp_f32_e32 v113, v92
	v_exp_f32_e32 v115, v93
	v_exp_f32_e32 v112, v94
	v_exp_f32_e32 v114, v95
	v_cndmask_b32_e64 v191, v134, 1.0, s[4:5]
	v_cmp_gt_f32_e32 vcc, 1.0, v191
	s_cbranch_vccz .LBB0_308
; #define SBAR() __builtin_amdgcn_sched_barrier(0)
; #define SLOAD(i, k0) do { sr_[i].vs0 = LD8(&Vh[(long)((k0) + sr) * LDK + sc]); sr_[i].vs1 = LD8(&Vh[(long)((k0) + 32 + sr) * LDK + sc]); \
;     sr_[i].ks0 = LD8(&Kh[(long)((k0) + sr) * LDK + sc]); sr_[i].ks1 = LD8(&Kh[(long)((k0) + 32 + sr) * LDK + sc]); \
;     sr_[i].kp = LD8(&KPh[(long)((k0) + pr) * LDKP + pc]); } while (0)
; #define RESC(a) do { if (__any((a) < 1.f)) { if (hi == 0) al_l[r32] = (a); asm volatile("s_waitcnt lgkmcnt(0)" ::: "memory"); \
;     _Pragma("unroll") for (int d = 0; d < 4; ++d) _Pragma("unroll") for (int r = 0; r < 16; ++r) o[d][r] *= al_l[crow(r, hi)]; } } while (0)
; DEV void attn_item(const u16* __restrict__ Qb, const u16* __restrict__ Kh, const u16* __restrict__ Vh, const u16* __restrict__ KPh,
;                    u16* __restrict__ Ob, int seq, char* lds) {
;     ...
;     RESC(alB); __syncthreads();
;     SBAR(); qkt(pA0, pA1, K_lds, KP_lds, qr, qpl, r32, hi);
;     finishSM(pB0, pB1, alB, l_reg, pa0, pa1, pa2, pa3); SBAR();
;     SLOAD(SE, (j + 2) * KVBLK); SBAR();
	s_and_saveexec_b64 s[8:9], s[6:7]
	ds_write_b32 v150, v191 offset:128
	s_or_b64 exec, exec, s[8:9]
	s_waitcnt lgkmcnt(0)
	v_add_u32_e32 v228, v139, v136
	ds_read_b128 v[208:211], v228 offset:224
	ds_read_b128 v[212:215], v228 offset:192
	ds_read_b128 v[216:219], v228 offset:160
	ds_read_b128 v[220:223], v228 offset:128
	s_waitcnt lgkmcnt(3)
	v_pk_mul_f32 v[12:13], v[12:13], v[208:209]
	s_waitcnt lgkmcnt(2)
	v_pk_mul_f32 v[8:9], v[8:9], v[212:213]
	s_waitcnt lgkmcnt(1)
	v_pk_mul_f32 v[4:5], v[4:5], v[216:217]
	v_pk_mul_f32 v[14:15], v[14:15], v[210:211]
	v_pk_mul_f32 v[10:11], v[10:11], v[214:215]
	v_pk_mul_f32 v[6:7], v[6:7], v[218:219]
	s_waitcnt lgkmcnt(0)
	v_pk_mul_f32 v[2:3], v[2:3], v[222:223]
	v_pk_mul_f32 v[0:1], v[0:1], v[220:221]
	v_pk_mul_f32 v[60:61], v[60:61], v[208:209]
	v_pk_mul_f32 v[56:57], v[56:57], v[212:213]
	v_pk_mul_f32 v[52:53], v[52:53], v[216:217]
	v_pk_mul_f32 v[62:63], v[62:63], v[210:211]
	v_pk_mul_f32 v[58:59], v[58:59], v[214:215]
	v_pk_mul_f32 v[54:55], v[54:55], v[218:219]
	v_pk_mul_f32 v[50:51], v[50:51], v[222:223]
	v_pk_mul_f32 v[48:49], v[48:49], v[220:221]
	v_pk_mul_f32 v[44:45], v[44:45], v[208:209]
	v_pk_mul_f32 v[40:41], v[40:41], v[212:213]
	v_pk_mul_f32 v[36:37], v[36:37], v[216:217]
	v_pk_mul_f32 v[46:47], v[46:47], v[210:211]
	v_pk_mul_f32 v[42:43], v[42:43], v[214:215]
	v_pk_mul_f32 v[38:39], v[38:39], v[218:219]
	v_pk_mul_f32 v[34:35], v[34:35], v[222:223]
	v_pk_mul_f32 v[32:33], v[32:33], v[220:221]
	v_pk_mul_f32 v[28:29], v[28:29], v[208:209]
	v_pk_mul_f32 v[24:25], v[24:25], v[212:213]
	v_pk_mul_f32 v[20:21], v[20:21], v[216:217]
	v_pk_mul_f32 v[30:31], v[30:31], v[210:211]
	v_pk_mul_f32 v[26:27], v[26:27], v[214:215]
	v_pk_mul_f32 v[22:23], v[22:23], v[218:219]
	v_pk_mul_f32 v[18:19], v[18:19], v[222:223]
	v_pk_mul_f32 v[16:17], v[16:17], v[220:221]
.LBB0_308:
	v_cndmask_b32_e64 v192, v133, v132, s[4:5]
	v_mul_f32_e32 v128, 0xbdd53b94, v192
	v_fmamk_f32 v132, v71, 0x3dd53b94, v128
	v_fmamk_f32 v133, v72, 0x3dd53b94, v128
	v_fmamk_f32 v194, v64, 0x3dd53b94, v128
	v_fmamk_f32 v195, v65, 0x3dd53b94, v128
	v_fmamk_f32 v196, v66, 0x3dd53b94, v128
	v_fmamk_f32 v197, v67, 0x3dd53b94, v128
	v_fmamk_f32 v198, v68, 0x3dd53b94, v128
	v_fmamk_f32 v130, v69, 0x3dd53b94, v128
	v_fmamk_f32 v131, v70, 0x3dd53b94, v128
	v_fmamk_f32 v134, v73, 0x3dd53b94, v128
	v_fmamk_f32 v135, v74, 0x3dd53b94, v128
	v_fmamk_f32 v193, v75, 0x3dd53b94, v128
	v_fmamk_f32 v129, v76, 0x3dd53b94, v128
	v_fmamk_f32 v199, v77, 0x3dd53b94, v128
	v_fmamk_f32 v200, v78, 0x3dd53b94, v128
	v_fmac_f32_e32 v128, 0x3dd53b94, v79
	s_waitcnt lgkmcnt(0)
	s_barrier
	s_waitcnt vmcnt(0)
	ds_write_b128 v154, v[238:241]
	ds_write_b128 v155, v[242:245]
	v_add_co_u32_e32 v224, vcc, s73, v142
	s_mov_b32 s0, 0x22000
	s_nop 0
	v_addc_co_u32_e32 v225, vcc, 0, v143, vcc
	v_add_co_u32_e32 v222, vcc, s74, v142
	s_nop 1
	v_addc_co_u32_e32 v223, vcc, 0, v143, vcc
	v_add_co_u32_e32 v220, vcc, s0, v140
	s_nop 1
	v_addc_co_u32_e32 v221, vcc, 0, v141, vcc
	global_load_dwordx4 v[226:229], v[224:225], off
	global_load_dwordx4 v[230:233], v[222:223], off
	global_load_dwordx4 v[234:237], v[220:221], off
	global_load_dwordx4 v[238:241], v[224:225], off offset:256
	global_load_dwordx4 v[242:245], v[222:223], off offset:256
	ds_read_b128 v[64:67], v159 offset:32768
	ds_read_b128 v[68:71], v159 offset:40960
	ds_read_b128 v[202:205], v162 offset:32768
	ds_read_b128 v[206:209], v162 offset:40960
	v_exp_f32_e32 v201, v194
	v_exp_f32_e32 v130, v130
	s_waitcnt lgkmcnt(3)
	v_mfma_f32_32x32x16_bf16 v[80:95], v[64:67], v[108:111], 0
	v_exp_f32_e32 v131, v131
	v_exp_f32_e32 v193, v193
	v_exp_f32_e32 v129, v129
	v_exp_f32_e32 v128, v128
	s_waitcnt lgkmcnt(2)
	v_mfma_f32_32x32x16_bf16 v[64:79], v[68:71], v[108:111], 0
	s_waitcnt lgkmcnt(0)
	v_mfma_f32_32x32x16_bf16 v[64:79], v[206:209], v[104:107], v[64:79]
	v_mfma_f32_32x32x16_bf16 v[80:95], v[202:205], v[104:107], v[80:95]
	ds_read_b128 v[202:205], v163 offset:32768
	ds_read_b128 v[206:209], v163 offset:40960
	s_waitcnt lgkmcnt(0)
	v_mfma_f32_32x32x16_bf16 v[64:79], v[206:209], v[100:103], v[64:79]
	v_mfma_f32_32x32x16_bf16 v[80:95], v[202:205], v[100:103], v[80:95]
	ds_read_b128 v[202:205], v166 offset:32768
	ds_read_b128 v[206:209], v166 offset:40960
	s_waitcnt lgkmcnt(0)
	v_mfma_f32_32x32x16_bf16 v[64:79], v[206:209], v[96:99], v[64:79]
	v_mfma_f32_32x32x16_bf16 v[80:95], v[202:205], v[96:99], v[80:95]
	ds_read_b128 v[202:205], v167 offset:32768
	ds_read_b128 v[206:209], v167 offset:40960
	ds_read_b128 v[210:213], v177
	s_waitcnt lgkmcnt(0)
	v_mfma_f32_32x32x16_bf16 v[64:79], v[206:209], v[210:213], v[64:79]
	v_mfma_f32_32x32x16_bf16 v[80:95], v[202:205], v[210:213], v[80:95]
	ds_read_b128 v[202:205], v168 offset:32768
	ds_read_b128 v[206:209], v168 offset:40960
	ds_read_b128 v[210:213], v177 offset:1024
	s_waitcnt lgkmcnt(0)
	v_mfma_f32_32x32x16_bf16 v[64:79], v[206:209], v[210:213], v[64:79]
	v_mfma_f32_32x32x16_bf16 v[80:95], v[202:205], v[210:213], v[80:95]
	ds_read_b128 v[202:205], v160 offset:32768
	ds_read_b128 v[206:209], v160 offset:40960
	ds_read_b128 v[210:213], v177 offset:2048
	s_waitcnt lgkmcnt(0)
	v_mfma_f32_32x32x16_bf16 v[64:79], v[206:209], v[210:213], v[64:79]
	v_mfma_f32_32x32x16_bf16 v[80:95], v[202:205], v[210:213], v[80:95]
	ds_read_b128 v[202:205], v161 offset:32768
	ds_read_b128 v[206:209], v161 offset:40960
	ds_read_b128 v[210:213], v177 offset:3072
	s_waitcnt lgkmcnt(0)
	v_mfma_f32_32x32x16_bf16 v[64:79], v[206:209], v[210:213], v[64:79]
	v_mfma_f32_32x32x16_bf16 v[80:95], v[202:205], v[210:213], v[80:95]
	ds_read_b128 v[202:205], v169
	ds_read_b128 v[206:209], v170
	ds_read_b128 v[210:213], v177 offset:4096
	s_waitcnt lgkmcnt(0)
; #define SBAR() __builtin_amdgcn_sched_barrier(0)
; #define SLOAD(i, k0) do { sr_[i].vs0 = LD8(&Vh[(long)((k0) + sr) * LDK + sc]); sr_[i].vs1 = LD8(&Vh[(long)((k0) + 32 + sr) * LDK + sc]); \
;     sr_[i].ks0 = LD8(&Kh[(long)((k0) + sr) * LDK + sc]); sr_[i].ks1 = LD8(&Kh[(long)((k0) + 32 + sr) * LDK + sc]); \
;     sr_[i].kp = LD8(&KPh[(long)((k0) + pr) * LDKP + pc]); } while (0)
; DEV void finishSM(f32x16& p0, f32x16& p1, float alpha, float& l_reg, bf16x8& pa0, bf16x8& pa1, bf16x8& pa2, bf16x8& pa3) {
; #pragma unroll
;   for (int r = 0; r < 16; ++r) p1[r] = __builtin_amdgcn_exp2f(p1[r]);
;   float ps = 0;
; #pragma unroll
;   for (int r = 0; r < 16; ++r) ps += p0[r];
; #pragma unroll
;   for (int r = 0; r < 16; ++r) ps += p1[r];
;   { auto rr = __builtin_amdgcn_permlane32_swap(__float_as_uint(ps), __float_as_uint(ps), false, false);
;     ps = __uint_as_float(rr[0]) + __uint_as_float(rr[1]); }
;   l_reg = l_reg * alpha + ps;
;     ...
;   PK4(p0, 0, pa0); PK4(p0, 8, pa1); PK4(p1, 0, pa2); PK4(p1, 8, pa3);
;     ...
; }
; DEV void attn_item(const u16* __restrict__ Qb, const u16* __restrict__ Kh, const u16* __restrict__ Vh, const u16* __restrict__ KPh,
;                    u16* __restrict__ Ob, int seq, char* lds) {
;     ...
;     SBAR(); qkt(pA0, pA1, K_lds, KP_lds, qr, qpl, r32, hi);
;     finishSM(pB0, pB1, alB, l_reg, pa0, pa1, pa2, pa3); SBAR();
;     SLOAD(SE, (j + 2) * KVBLK); SBAR();
;     pv_d0(o, vb0 + SHM_V, pa0, pa1, pa2, pa3); partialSM(pA0, pA1, m_reg, mnA, alA);
	v_mfma_f32_32x32x16_bf16 v[64:79], v[206:209], v[210:213], v[64:79]
	v_mfma_f32_32x32x16_bf16 v[80:95], v[202:205], v[210:213], v[80:95]
	ds_read_b128 v[202:205], v171
	ds_read_b128 v[206:209], v172
	ds_read_b128 v[210:213], v177 offset:5120
	s_waitcnt lgkmcnt(0)
	v_mfma_f32_32x32x16_bf16 v[64:79], v[206:209], v[210:213], v[64:79]
	v_mfma_f32_32x32x16_bf16 v[80:95], v[202:205], v[210:213], v[80:95]
	ds_read_b128 v[202:205], v173
	ds_read_b128 v[206:209], v174
	ds_read_b128 v[210:213], v177 offset:6144
	s_waitcnt lgkmcnt(0)
	v_mfma_f32_32x32x16_bf16 v[64:79], v[206:209], v[210:213], v[64:79]
	v_mfma_f32_32x32x16_bf16 v[80:95], v[202:205], v[210:213], v[80:95]
	ds_read_b128 v[202:205], v176
	ds_read_b128 v[206:209], v178
	ds_read_b128 v[210:213], v177 offset:7168
	s_waitcnt lgkmcnt(0)
	v_mfma_f32_32x32x16_bf16 v[64:79], v[206:209], v[210:213], v[64:79]
	v_exp_f32_e32 v208, v132
	v_add_f32_e32 v132, 0, v125
	v_add_f32_e32 v132, v127, v132
	v_add_f32_e32 v132, v123, v132
	v_add_f32_e32 v132, v126, v132
	v_add_f32_e32 v132, v122, v132
	v_add_f32_e32 v132, v124, v132
	v_add_f32_e32 v132, v120, v132
	v_add_f32_e32 v132, v121, v132
	v_add_f32_e32 v132, v117, v132
	v_add_f32_e32 v132, v119, v132
	v_add_f32_e32 v132, v116, v132
	v_add_f32_e32 v132, v118, v132
	v_add_f32_e32 v132, v113, v132
	v_mfma_f32_32x32x16_bf16 v[80:95], v[202:205], v[210:213], v[80:95]
	v_exp_f32_e32 v204, v195
	v_add_f32_e32 v132, v115, v132
	v_exp_f32_e32 v205, v196
	v_add_f32_e32 v132, v112, v132
	v_exp_f32_e32 v206, v197
	v_add_f32_e32 v132, v114, v132
	v_exp_f32_e32 v207, v198
	v_add_f32_e32 v132, v201, v132
	v_add_f32_e32 v132, v204, v132
	v_add_f32_e32 v132, v205, v132
	v_add_f32_e32 v132, v206, v132
	v_exp_f32_e32 v209, v133
	v_add_f32_e32 v132, v207, v132
	v_exp_f32_e32 v210, v134
	v_add_f32_e32 v132, v130, v132
	v_exp_f32_e32 v211, v135
	v_add_f32_e32 v132, v131, v132
	v_add_f32_e32 v132, v208, v132
	v_add_f32_e32 v132, v209, v132
	v_exp_f32_e32 v212, v199
	v_add_f32_e32 v132, v210, v132
	v_exp_f32_e32 v213, v200
	v_add_f32_e32 v132, v211, v132
	v_add_f32_e32 v132, v193, v132
	v_add_f32_e32 v132, v129, v132
	v_add_f32_e32 v132, v212, v132
	v_add_f32_e32 v132, v213, v132
	v_add_f32_e32 v202, v128, v132
	v_mov_b32_e32 v203, v202
	v_cvt_pk_bf16_f32 v132, v125, v127
	v_cvt_pk_bf16_f32 v133, v123, v126
	v_cvt_pk_bf16_f32 v134, v122, v124
	v_cvt_pk_bf16_f32 v135, v120, v121
	s_nop 1
	v_permlane32_swap_b32_e32 v202, v203
	v_permlane32_swap_b32_e32 v132, v134
	v_permlane32_swap_b32_e32 v133, v135
	v_cvt_pk_bf16_f32 v194, v117, v119
	v_cvt_pk_bf16_f32 v195, v116, v118
	v_cvt_pk_bf16_f32 v196, v113, v115
	v_cvt_pk_bf16_f32 v197, v112, v114
	v_cvt_pk_bf16_f32 v198, v201, v204
	v_cvt_pk_bf16_f32 v199, v205, v206
	v_cvt_pk_bf16_f32 v200, v207, v130
	v_cvt_pk_bf16_f32 v201, v131, v208
	v_cvt_pk_bf16_f32 v204, v209, v210
	v_cvt_pk_bf16_f32 v205, v211, v193
	v_cvt_pk_bf16_f32 v206, v129, v212
	v_cvt_pk_bf16_f32 v207, v213, v128
	s_nop 0
	v_permlane32_swap_b32_e32 v194, v196
	v_permlane32_swap_b32_e32 v195, v197
	v_permlane32_swap_b32_e32 v198, v200
	v_permlane32_swap_b32_e32 v199, v201
	v_permlane32_swap_b32_e32 v204, v206
	v_permlane32_swap_b32_e32 v205, v207
	s_waitcnt vmcnt(2)
	ds_write_b128 v156, v[226:229] offset:49152
	ds_write_b128 v157, v[230:233] offset:49152
	ds_write_b128 v183, v[234:237]
	ds_read_b64_tr_b16 v[208:209], v152 offset:0
	ds_read_b64_tr_b16 v[210:211], v152 offset:0x800
	ds_read_b64_tr_b16 v[212:213], v152 offset:0x1000
	ds_read_b64_tr_b16 v[214:215], v152 offset:0x1800
	ds_read_b64_tr_b16 v[216:217], v152 offset:0x2000
	ds_read_b64_tr_b16 v[218:219], v152 offset:0x2800
	ds_read_b64_tr_b16 v[220:221], v152 offset:0x3000
	ds_read_b64_tr_b16 v[222:223], v152 offset:0x3800
	s_waitcnt lgkmcnt(6)
	s_nop 0
	v_mfma_f32_32x32x16_bf16 v[0:15], v[132:135], v[208:211], v[0:15]
	ds_read_b64_tr_b16 v[208:209], v152 offset:0x200
	ds_read_b64_tr_b16 v[210:211], v152 offset:0xa00
	s_waitcnt lgkmcnt(6)
	v_mfma_f32_32x32x16_bf16 v[0:15], v[194:197], v[212:215], v[0:15]
	ds_read_b64_tr_b16 v[212:213], v152 offset:0x1200
	ds_read_b64_tr_b16 v[214:215], v152 offset:0x1a00
	s_waitcnt lgkmcnt(6)
	v_mfma_f32_32x32x16_bf16 v[0:15], v[198:201], v[216:219], v[0:15]
	ds_read_b64_tr_b16 v[216:217], v152 offset:0x2200
	ds_read_b64_tr_b16 v[218:219], v152 offset:0x2a00
	s_waitcnt lgkmcnt(6)
	v_mfma_f32_32x32x16_bf16 v[0:15], v[204:207], v[220:223], v[0:15]
	ds_read_b64_tr_b16 v[220:221], v152 offset:0x3200
	ds_read_b64_tr_b16 v[222:223], v152 offset:0x3a00
	s_waitcnt lgkmcnt(6)
	v_mfma_f32_32x32x16_bf16 v[48:63], v[132:135], v[208:211], v[48:63]
	ds_read_b64_tr_b16 v[208:209], v152 offset:0x400
	ds_read_b64_tr_b16 v[210:211], v152 offset:0xc00
	s_waitcnt lgkmcnt(6)
; #define SWAIT() asm volatile("s_waitcnt vmcnt(0)" ::: "memory")
; #define RESC(a) do { if (__any((a) < 1.f)) { if (hi == 0) al_l[r32] = (a); asm volatile("s_waitcnt lgkmcnt(0)" ::: "memory"); \
;     _Pragma("unroll") for (int d = 0; d < 4; ++d) _Pragma("unroll") for (int r = 0; r < 16; ++r) o[d][r] *= al_l[crow(r, hi)]; } } while (0)
; DEV void partialSM(f32x16& p0, f32x16& p1, float& m_reg, float& mn, float& alpha) {
;   constexpr float C = SCALE * 1.4426950408889634f;
;   float pmax = p0[0];
; #pragma unroll
;   for (int r = 1; r < 16; ++r) pmax = fmaxf(pmax, p0[r]);
; #pragma unroll
;   for (int r = 0; r < 16; ++r) pmax = fmaxf(pmax, p1[r]);
;   { auto rr = __builtin_amdgcn_permlane32_swap(__float_as_uint(pmax), __float_as_uint(pmax), false, false);
;     pmax = fmaxf(__uint_as_float(rr[0]), __uint_as_float(rr[1])); }
;   if (__builtin_expect(__all(pmax - m_reg <= THR / SCALE), 1)) { mn = m_reg; alpha = 1.f; }
;   else { mn = fmaxf(m_reg, pmax); alpha = __builtin_amdgcn_exp2f((m_reg - mn) * C); m_reg = mn; }
; DEV void attn_item(const u16* __restrict__ Qb, const u16* __restrict__ Kh, const u16* __restrict__ Vh, const u16* __restrict__ KPh,
;                    u16* __restrict__ Ob, int seq, char* lds) {
;     ...
;     pv_d0(o, vb0 + SHM_V, pa0, pa1, pa2, pa3); partialSM(pA0, pA1, m_reg, mnA, alA);
;     __syncthreads(); SWAIT(); SWRITE(1, SO);
;     RESC(alA); __syncthreads();
	v_mfma_f32_32x32x16_bf16 v[48:63], v[194:197], v[212:215], v[48:63]
	ds_read_b64_tr_b16 v[212:213], v152 offset:0x1400
	ds_read_b64_tr_b16 v[214:215], v152 offset:0x1c00
	s_waitcnt lgkmcnt(6)
	v_mfma_f32_32x32x16_bf16 v[48:63], v[198:201], v[216:219], v[48:63]
	ds_read_b64_tr_b16 v[216:217], v152 offset:0x2400
	ds_read_b64_tr_b16 v[218:219], v152 offset:0x2c00
	s_waitcnt lgkmcnt(6)
	v_mfma_f32_32x32x16_bf16 v[48:63], v[204:207], v[220:223], v[48:63]
	ds_read_b64_tr_b16 v[220:221], v152 offset:0x3400
	ds_read_b64_tr_b16 v[222:223], v152 offset:0x3c00
	s_waitcnt lgkmcnt(6)
	v_mfma_f32_32x32x16_bf16 v[32:47], v[132:135], v[208:211], v[32:47]
	ds_read_b64_tr_b16 v[208:209], v152 offset:0x600
	ds_read_b64_tr_b16 v[210:211], v152 offset:0xe00
	s_waitcnt lgkmcnt(6)
	v_mfma_f32_32x32x16_bf16 v[32:47], v[194:197], v[212:215], v[32:47]
	ds_read_b64_tr_b16 v[212:213], v152 offset:0x1600
	ds_read_b64_tr_b16 v[214:215], v152 offset:0x1e00
	s_waitcnt lgkmcnt(6)
	v_mfma_f32_32x32x16_bf16 v[32:47], v[198:201], v[216:219], v[32:47]
	ds_read_b64_tr_b16 v[216:217], v152 offset:0x2600
	ds_read_b64_tr_b16 v[218:219], v152 offset:0x2e00
	s_waitcnt lgkmcnt(6)
	v_mfma_f32_32x32x16_bf16 v[32:47], v[204:207], v[220:223], v[32:47]
	ds_read_b64_tr_b16 v[220:221], v152 offset:0x3600
	ds_read_b64_tr_b16 v[222:223], v152 offset:0x3e00
	s_waitcnt lgkmcnt(6)
	v_mfma_f32_32x32x16_bf16 v[16:31], v[132:135], v[208:211], v[16:31]
	v_max_f32_e32 v132, v81, v81
	v_max_f32_e32 v133, v80, v80
	v_max_f32_e32 v132, v133, v132
	v_max3_f32 v132, v132, v82, v83
	v_max3_f32 v132, v132, v84, v85
	v_max3_f32 v132, v132, v86, v87
	v_max3_f32 v132, v132, v88, v89
	v_max3_f32 v132, v132, v90, v91
	v_max3_f32 v132, v132, v92, v93
	s_waitcnt lgkmcnt(4)
	v_mfma_f32_32x32x16_bf16 v[16:31], v[194:197], v[212:215], v[16:31]
	v_max3_f32 v132, v132, v94, v95
	v_max3_f32 v132, v132, v64, v65
	v_max3_f32 v132, v132, v66, v67
	v_max3_f32 v132, v132, v68, v69
	v_max3_f32 v132, v132, v70, v71
	v_max3_f32 v132, v132, v72, v73
	v_max3_f32 v132, v132, v74, v75
	v_max3_f32 v132, v132, v76, v77
	s_waitcnt lgkmcnt(2)
	v_mfma_f32_32x32x16_bf16 v[16:31], v[198:201], v[216:219], v[16:31]
	v_max3_f32 v132, v132, v78, v79
	v_mov_b32_e32 v133, v132
	s_nop 1
	v_permlane32_swap_b32_e32 v132, v133
	v_max_f32_e32 v133, v133, v133
	v_max_f32_e32 v132, v132, v132
	v_max_f32_e32 v132, v132, v133
	v_sub_f32_e32 v133, v132, v192
	v_cmp_ge_f32_e32 vcc, s72, v133
	v_max_f32_e32 v133, v192, v192
	v_max_f32_e32 v132, v133, v132
	s_waitcnt lgkmcnt(0)
	v_mfma_f32_32x32x16_bf16 v[16:31], v[204:207], v[220:223], v[16:31]
	v_sub_f32_e32 v133, v192, v132
	v_mul_f32_e32 v133, 0x3dd53b94, v133
	v_exp_f32_e32 v133, v133
	s_cmp_eq_u64 vcc, exec
	s_cselect_b64 s[4:5], -1, 0
	v_cndmask_b32_e64 v133, v133, 1.0, s[4:5]
	v_cmp_gt_f32_e32 vcc, 1.0, v133
	s_cbranch_vccz .LBB0_312
	s_and_saveexec_b64 s[8:9], s[6:7]
	ds_write_b32 v150, v133 offset:128
	s_or_b64 exec, exec, s[8:9]
	s_waitcnt lgkmcnt(0)
	v_add_u32_e32 v124, v139, v136
	ds_read_b128 v[112:115], v124 offset:224
	ds_read_b128 v[116:119], v124 offset:192
	ds_read_b128 v[120:123], v124 offset:160
	ds_read_b128 v[124:127], v124 offset:128
	s_waitcnt lgkmcnt(3)
	v_pk_mul_f32 v[12:13], v[12:13], v[112:113]
	s_waitcnt lgkmcnt(2)
	v_pk_mul_f32 v[8:9], v[8:9], v[116:117]
	s_waitcnt lgkmcnt(1)
	v_pk_mul_f32 v[4:5], v[4:5], v[120:121]
	v_pk_mul_f32 v[14:15], v[14:15], v[114:115]
	v_pk_mul_f32 v[10:11], v[10:11], v[118:119]
	v_pk_mul_f32 v[6:7], v[6:7], v[122:123]
	s_waitcnt lgkmcnt(0)
	v_pk_mul_f32 v[2:3], v[2:3], v[126:127]
	v_pk_mul_f32 v[0:1], v[0:1], v[124:125]
	v_pk_mul_f32 v[60:61], v[60:61], v[112:113]
	v_pk_mul_f32 v[56:57], v[56:57], v[116:117]
	v_pk_mul_f32 v[52:53], v[52:53], v[120:121]
	v_pk_mul_f32 v[62:63], v[62:63], v[114:115]
	v_pk_mul_f32 v[58:59], v[58:59], v[118:119]
	v_pk_mul_f32 v[54:55], v[54:55], v[122:123]
	v_pk_mul_f32 v[50:51], v[50:51], v[126:127]
	v_pk_mul_f32 v[48:49], v[48:49], v[124:125]
	v_pk_mul_f32 v[44:45], v[44:45], v[112:113]
	v_pk_mul_f32 v[40:41], v[40:41], v[116:117]
	v_pk_mul_f32 v[36:37], v[36:37], v[120:121]
	v_pk_mul_f32 v[46:47], v[46:47], v[114:115]
	v_pk_mul_f32 v[42:43], v[42:43], v[118:119]
	v_pk_mul_f32 v[38:39], v[38:39], v[122:123]
	v_pk_mul_f32 v[34:35], v[34:35], v[126:127]
	v_pk_mul_f32 v[32:33], v[32:33], v[124:125]
	v_pk_mul_f32 v[28:29], v[28:29], v[112:113]
	v_pk_mul_f32 v[24:25], v[24:25], v[116:117]
	v_pk_mul_f32 v[20:21], v[20:21], v[120:121]
	v_pk_mul_f32 v[30:31], v[30:31], v[114:115]
	v_pk_mul_f32 v[26:27], v[26:27], v[118:119]
	v_pk_mul_f32 v[22:23], v[22:23], v[122:123]
	v_pk_mul_f32 v[18:19], v[18:19], v[126:127]
	v_pk_mul_f32 v[16:17], v[16:17], v[124:125]

; #define SBAR() __builtin_amdgcn_sched_barrier(0)
; DEV void attn_item(const u16* __restrict__ Qb, const u16* __restrict__ Kh, const u16* __restrict__ Vh, const u16* __restrict__ KPh,
;                    u16* __restrict__ Ob, int seq, char* lds) {
;     ...
;   SBAR(); qkt(pB0, pB1, K_lds + SHM_K, KP_lds + SHM_KP, qr, qpl, r32, hi);
;   finishSM(pA0, pA1, alA, l_reg, pa0, pa1, pa2, pa3); SBAR();
;   pv_d0(o, vb0, pa0, pa1, pa2, pa3); partialSM(pB0, pB1, m_reg, mnB, alB);
.LBB0_314:
	s_waitcnt vmcnt(0)
	ds_write_b128 v154, v[238:241] offset:16384
	ds_write_b128 v155, v[242:245] offset:16384
	ds_read_b128 v[64:67], v159 offset:49152
	ds_read_b128 v[68:71], v159 offset:57344
	v_exp_f32_e32 v116, v116
	v_exp_f32_e32 v117, v117
	v_exp_f32_e32 v112, v112
	s_waitcnt lgkmcnt(1)
	v_mfma_f32_32x32x16_bf16 v[80:95], v[64:67], v[108:111], 0
	v_exp_f32_e32 v113, v113
	v_exp_f32_e32 v118, v118
	v_exp_f32_e32 v119, v119
	v_exp_f32_e32 v114, v114
	v_exp_f32_e32 v115, v115
	s_waitcnt lgkmcnt(0)
	v_mfma_f32_32x32x16_bf16 v[64:79], v[68:71], v[108:111], 0
	ds_read_b128 v[108:111], v162 offset:49152
	ds_read_b128 v[140:143], v162 offset:57344
	s_waitcnt lgkmcnt(1)
	v_mfma_f32_32x32x16_bf16 v[80:95], v[108:111], v[104:107], v[80:95]
	s_waitcnt lgkmcnt(0)
	v_mfma_f32_32x32x16_bf16 v[64:79], v[140:143], v[104:107], v[64:79]
	ds_read_b128 v[104:107], v163 offset:49152
	ds_read_b128 v[108:111], v163 offset:57344
	s_waitcnt lgkmcnt(1)
	v_mfma_f32_32x32x16_bf16 v[80:95], v[104:107], v[100:103], v[80:95]
	s_waitcnt lgkmcnt(0)
	v_mfma_f32_32x32x16_bf16 v[64:79], v[108:111], v[100:103], v[64:79]
	ds_read_b128 v[100:103], v166 offset:49152
	ds_read_b128 v[104:107], v166 offset:57344
	v_exp_f32_e32 v108, v124
	v_exp_f32_e32 v109, v125
	v_exp_f32_e32 v110, v120
	v_exp_f32_e32 v111, v121
	v_exp_f32_e32 v120, v122
	v_exp_f32_e32 v121, v123
	s_waitcnt lgkmcnt(1)
	v_mfma_f32_32x32x16_bf16 v[80:95], v[100:103], v[96:99], v[80:95]
	s_waitcnt lgkmcnt(0)
	v_mfma_f32_32x32x16_bf16 v[64:79], v[104:107], v[96:99], v[64:79]
	ds_read_b128 v[96:99], v167 offset:49152
	ds_read_b128 v[100:103], v167 offset:57344
	ds_read_b128 v[104:107], v177
	s_waitcnt lgkmcnt(0)
	v_mfma_f32_32x32x16_bf16 v[80:95], v[96:99], v[104:107], v[80:95]
	v_mfma_f32_32x32x16_bf16 v[64:79], v[100:103], v[104:107], v[64:79]
	ds_read_b128 v[96:99], v168 offset:49152
	ds_read_b128 v[100:103], v168 offset:57344
	ds_read_b128 v[104:107], v177 offset:1024
	s_waitcnt lgkmcnt(0)
	v_mfma_f32_32x32x16_bf16 v[80:95], v[96:99], v[104:107], v[80:95]
	v_mfma_f32_32x32x16_bf16 v[64:79], v[100:103], v[104:107], v[64:79]
	ds_read_b128 v[96:99], v160 offset:49152
	ds_read_b128 v[100:103], v160 offset:57344
	ds_read_b128 v[104:107], v177 offset:2048
	s_waitcnt lgkmcnt(0)
	v_mfma_f32_32x32x16_bf16 v[80:95], v[96:99], v[104:107], v[80:95]
	v_mfma_f32_32x32x16_bf16 v[64:79], v[100:103], v[104:107], v[64:79]
	ds_read_b128 v[96:99], v161 offset:49152
	ds_read_b128 v[100:103], v161 offset:57344
	ds_read_b128 v[104:107], v177 offset:3072
	s_waitcnt lgkmcnt(0)
	v_mfma_f32_32x32x16_bf16 v[80:95], v[96:99], v[104:107], v[80:95]
	v_mfma_f32_32x32x16_bf16 v[64:79], v[100:103], v[104:107], v[64:79]
	ds_read_b128 v[96:99], v184
	ds_read_b128 v[100:103], v185
	ds_read_b128 v[104:107], v177 offset:4096
	s_waitcnt lgkmcnt(0)
	v_mfma_f32_32x32x16_bf16 v[80:95], v[96:99], v[104:107], v[80:95]
	v_mfma_f32_32x32x16_bf16 v[64:79], v[100:103], v[104:107], v[64:79]
	ds_read_b128 v[96:99], v181
	ds_read_b128 v[100:103], v182
	ds_read_b128 v[104:107], v177 offset:5120
	s_waitcnt lgkmcnt(0)
	v_mfma_f32_32x32x16_bf16 v[80:95], v[96:99], v[104:107], v[80:95]
	v_mfma_f32_32x32x16_bf16 v[64:79], v[100:103], v[104:107], v[64:79]
	ds_read_b128 v[96:99], v179
	ds_read_b128 v[100:103], v180
	ds_read_b128 v[104:107], v177 offset:6144
	s_waitcnt lgkmcnt(0)
	v_mfma_f32_32x32x16_bf16 v[80:95], v[96:99], v[104:107], v[80:95]
	v_mfma_f32_32x32x16_bf16 v[64:79], v[100:103], v[104:107], v[64:79]
	ds_read_b128 v[96:99], v187
	ds_read_b128 v[100:103], v188
	ds_read_b128 v[104:107], v177 offset:7168
	s_waitcnt lgkmcnt(0)
	v_mfma_f32_32x32x16_bf16 v[80:95], v[96:99], v[104:107], v[80:95]
	v_add_f32_e32 v96, 0, v196
	v_add_f32_e32 v96, v199, v96
	v_add_f32_e32 v96, v197, v96
	v_add_f32_e32 v96, v200, v96
	v_add_f32_e32 v96, v198, v96
	v_add_f32_e32 v96, v201, v96
	v_add_f32_e32 v96, v194, v96
	v_add_f32_e32 v96, v195, v96
	v_add_f32_e32 v96, v134, v96
	v_add_f32_e32 v96, v192, v96
	v_add_f32_e32 v96, v135, v96
	v_add_f32_e32 v96, v193, v96
	v_mfma_f32_32x32x16_bf16 v[64:79], v[100:103], v[104:107], v[64:79]
	v_exp_f32_e32 v106, v126
	v_add_f32_e32 v96, v128, v96
	v_exp_f32_e32 v107, v127
	v_add_f32_e32 v96, v130, v96
	v_add_f32_e32 v96, v129, v96
	v_add_f32_e32 v96, v131, v96
	v_add_f32_e32 v96, v106, v96
	v_add_f32_e32 v96, v107, v96
	v_add_f32_e32 v96, v108, v96
	v_add_f32_e32 v96, v109, v96
	v_add_f32_e32 v96, v110, v96
	v_add_f32_e32 v96, v111, v96
	v_add_f32_e32 v96, v116, v96
	v_add_f32_e32 v96, v117, v96
	v_add_f32_e32 v96, v112, v96
	v_add_f32_e32 v96, v113, v96
	v_add_f32_e32 v96, v120, v96
	v_add_f32_e32 v96, v121, v96
	v_add_f32_e32 v96, v118, v96
	v_add_f32_e32 v96, v119, v96
	v_add_f32_e32 v96, v114, v96
	v_add_f32_e32 v96, v115, v96
	v_mov_b32_e32 v97, v96
	v_cvt_pk_bf16_f32 v98, v196, v199
	v_cvt_pk_bf16_f32 v99, v197, v200
	v_cvt_pk_bf16_f32 v100, v198, v201
	v_cvt_pk_bf16_f32 v101, v194, v195
	s_nop 1
	v_permlane32_swap_b32_e32 v96, v97
	v_permlane32_swap_b32_e32 v98, v100
	v_permlane32_swap_b32_e32 v99, v101
	v_cvt_pk_bf16_f32 v102, v134, v192
	v_cvt_pk_bf16_f32 v103, v135, v193
	v_cvt_pk_bf16_f32 v104, v128, v130
	v_cvt_pk_bf16_f32 v105, v129, v131
	v_cvt_pk_bf16_f32 v106, v106, v107
	v_cvt_pk_bf16_f32 v107, v108, v109
	v_cvt_pk_bf16_f32 v108, v110, v111
	v_cvt_pk_bf16_f32 v109, v116, v117
	v_cvt_pk_bf16_f32 v110, v112, v113
	v_cvt_pk_bf16_f32 v111, v120, v121
	v_cvt_pk_bf16_f32 v112, v118, v119
	v_cvt_pk_bf16_f32 v113, v114, v115
	s_nop 0
	v_permlane32_swap_b32_e32 v102, v104
	v_permlane32_swap_b32_e32 v103, v105
	v_permlane32_swap_b32_e32 v106, v108
	v_permlane32_swap_b32_e32 v107, v109
	v_permlane32_swap_b32_e32 v110, v112
	v_permlane32_swap_b32_e32 v111, v113
	ds_read_b64_tr_b16 v[114:115], v153 offset:0
	ds_read_b64_tr_b16 v[116:117], v153 offset:0x800
	ds_read_b64_tr_b16 v[118:119], v153 offset:0x1000
	ds_read_b64_tr_b16 v[120:121], v153 offset:0x1800
	ds_read_b64_tr_b16 v[122:123], v153 offset:0x2000
	ds_read_b64_tr_b16 v[124:125], v153 offset:0x2800
	ds_read_b64_tr_b16 v[126:127], v153 offset:0x3000
	ds_read_b64_tr_b16 v[128:129], v153 offset:0x3800
	s_waitcnt lgkmcnt(0)
; #define SBAR() __builtin_amdgcn_sched_barrier(0)
; DEV void partialSM(f32x16& p0, f32x16& p1, float& m_reg, float& mn, float& alpha) {
;   constexpr float C = SCALE * 1.4426950408889634f;
;   float pmax = p0[0];
; #pragma unroll
;   for (int r = 1; r < 16; ++r) pmax = fmaxf(pmax, p0[r]);
; #pragma unroll
;   for (int r = 0; r < 16; ++r) pmax = fmaxf(pmax, p1[r]);
;   { auto rr = __builtin_amdgcn_permlane32_swap(__float_as_uint(pmax), __float_as_uint(pmax), false, false);
;     pmax = fmaxf(__uint_as_float(rr[0]), __uint_as_float(rr[1])); }
;   if (__builtin_expect(__all(pmax - m_reg <= THR / SCALE), 1)) { mn = m_reg; alpha = 1.f; }
;   else { mn = fmaxf(m_reg, pmax); alpha = __builtin_amdgcn_exp2f((m_reg - mn) * C); m_reg = mn; }
; template <int D0> DEV void pv_one(f32x16& od, int vb, bf16x8 pa0, bf16x8 pa1, bf16x8 pa2, bf16x8 pa3) {
;   const s16x4 l0 = tr_read<v_rd_off(D0, 0, 0)>(vb), h0 = tr_read<v_rd_off(D0, 0, 1)>(vb), l1 = tr_read<v_rd_off(D0, 1, 0)>(vb), h1 = tr_read<v_rd_off(D0, 1, 1)>(vb);
;   const s16x4 l2 = tr_read<v_rd_off(D0, 2, 0)>(vb), h2 = tr_read<v_rd_off(D0, 2, 1)>(vb), l3 = tr_read<v_rd_off(D0, 3, 0)>(vb), h3 = tr_read<v_rd_off(D0, 3, 1)>(vb);
;   asm volatile("s_waitcnt lgkmcnt(0)" ::: "memory"); SBAR();
;     ...
;   od = __builtin_amdgcn_mfma_f32_32x32x16_bf16(pa0, PK(l0, h0), od, 0, 0, 0);
;   od = __builtin_amdgcn_mfma_f32_32x32x16_bf16(pa1, PK(l1, h1), od, 0, 0, 0);
;   od = __builtin_amdgcn_mfma_f32_32x32x16_bf16(pa2, PK(l2, h2), od, 0, 0, 0);
;   od = __builtin_amdgcn_mfma_f32_32x32x16_bf16(pa3, PK(l3, h3), od, 0, 0, 0);
;     ...
; }
; DEV void pv_d0(f32x16* o, int vb, bf16x8 pa0, bf16x8 pa1, bf16x8 pa2, bf16x8 pa3) {
;   pv_one<0>(o[0], vb, pa0, pa1, pa2, pa3); pv_one<1>(o[1], vb, pa0, pa1, pa2, pa3); pv_one<2>(o[2], vb, pa0, pa1, pa2, pa3); pv_one<3>(o[3], vb, pa0, pa1, pa2, pa3);
	s_nop 0
	v_mfma_f32_32x32x16_bf16 v[0:15], v[98:101], v[114:117], v[0:15]
	ds_read_b64_tr_b16 v[114:115], v153 offset:0x200
	ds_read_b64_tr_b16 v[116:117], v153 offset:0xa00
	v_mfma_f32_32x32x16_bf16 v[0:15], v[102:105], v[118:121], v[0:15]
	ds_read_b64_tr_b16 v[118:119], v153 offset:0x1200
	ds_read_b64_tr_b16 v[120:121], v153 offset:0x1a00
	v_mfma_f32_32x32x16_bf16 v[0:15], v[106:109], v[122:125], v[0:15]
	ds_read_b64_tr_b16 v[122:123], v153 offset:0x2200
	ds_read_b64_tr_b16 v[124:125], v153 offset:0x2a00
	v_mfma_f32_32x32x16_bf16 v[0:15], v[110:113], v[126:129], v[0:15]
	ds_read_b64_tr_b16 v[126:127], v153 offset:0x3200
	ds_read_b64_tr_b16 v[128:129], v153 offset:0x3a00
	s_waitcnt lgkmcnt(0)
	v_mfma_f32_32x32x16_bf16 v[48:63], v[98:101], v[114:117], v[48:63]
	ds_read_b64_tr_b16 v[114:115], v153 offset:0x400
	ds_read_b64_tr_b16 v[116:117], v153 offset:0xc00
	v_mfma_f32_32x32x16_bf16 v[48:63], v[102:105], v[118:121], v[48:63]
	ds_read_b64_tr_b16 v[118:119], v153 offset:0x1400
	ds_read_b64_tr_b16 v[120:121], v153 offset:0x1c00
	v_mfma_f32_32x32x16_bf16 v[48:63], v[106:109], v[122:125], v[48:63]
	ds_read_b64_tr_b16 v[122:123], v153 offset:0x2400
	ds_read_b64_tr_b16 v[124:125], v153 offset:0x2c00
	v_mfma_f32_32x32x16_bf16 v[48:63], v[110:113], v[126:129], v[48:63]
	ds_read_b64_tr_b16 v[126:127], v153 offset:0x3400
	ds_read_b64_tr_b16 v[128:129], v153 offset:0x3c00
	s_waitcnt lgkmcnt(0)
	v_mfma_f32_32x32x16_bf16 v[32:47], v[98:101], v[114:117], v[32:47]
	ds_read_b64_tr_b16 v[114:115], v153 offset:0x600
	ds_read_b64_tr_b16 v[116:117], v153 offset:0xe00
	v_mfma_f32_32x32x16_bf16 v[32:47], v[102:105], v[118:121], v[32:47]
	ds_read_b64_tr_b16 v[118:119], v153 offset:0x1600
	ds_read_b64_tr_b16 v[120:121], v153 offset:0x1e00
	v_mfma_f32_32x32x16_bf16 v[32:47], v[106:109], v[122:125], v[32:47]
	ds_read_b64_tr_b16 v[122:123], v153 offset:0x2600
	ds_read_b64_tr_b16 v[124:125], v153 offset:0x2e00
	v_mfma_f32_32x32x16_bf16 v[32:47], v[110:113], v[126:129], v[32:47]
	ds_read_b64_tr_b16 v[126:127], v153 offset:0x3600
	ds_read_b64_tr_b16 v[128:129], v153 offset:0x3e00
	s_waitcnt lgkmcnt(0)
	v_mfma_f32_32x32x16_bf16 v[16:31], v[98:101], v[114:117], v[16:31]
	v_max_f32_e32 v98, v81, v81
	v_max_f32_e32 v99, v80, v80
	v_max_f32_e32 v98, v99, v98
	v_max3_f32 v98, v98, v82, v83
	v_max3_f32 v98, v98, v84, v85
	v_max3_f32 v98, v98, v86, v87
	v_max3_f32 v98, v98, v88, v89
	v_max3_f32 v98, v98, v90, v91
	v_max3_f32 v98, v98, v92, v93
	v_mfma_f32_32x32x16_bf16 v[16:31], v[102:105], v[118:121], v[16:31]
	v_max3_f32 v98, v98, v94, v95
	v_max3_f32 v98, v98, v64, v65
	v_max3_f32 v98, v98, v66, v67
	v_max3_f32 v98, v98, v68, v69
	v_max3_f32 v98, v98, v70, v71
	v_max3_f32 v98, v98, v72, v73
	v_max3_f32 v98, v98, v74, v75
	v_max3_f32 v98, v98, v76, v77
	v_mfma_f32_32x32x16_bf16 v[16:31], v[106:109], v[122:125], v[16:31]
	v_max3_f32 v98, v98, v78, v79
	v_mov_b32_e32 v99, v98
	s_nop 1
	v_permlane32_swap_b32_e32 v98, v99
	v_max_f32_e32 v99, v99, v99
	v_max_f32_e32 v98, v98, v98
	v_max_f32_e32 v98, v98, v99
	v_sub_f32_e32 v99, v98, v132
	v_cmp_ge_f32_e32 vcc, s72, v99
	v_max_f32_e32 v99, v132, v132
	v_max_f32_e32 v99, v99, v98
	v_mfma_f32_32x32x16_bf16 v[16:31], v[110:113], v[126:129], v[16:31]
	v_sub_f32_e32 v98, v132, v99
	v_mul_f32_e32 v98, 0x3dd53b94, v98
	v_exp_f32_e32 v98, v98
	s_cmp_eq_u64 vcc, exec
	s_cselect_b64 s[4:5], -1, 0
	v_cndmask_b32_e64 v98, v98, 1.0, s[4:5]
	v_cmp_gt_f32_e32 vcc, 1.0, v98
	s_barrier
	s_cbranch_vccz .LBB0_318
	s_and_saveexec_b64 s[8:9], s[6:7]
	ds_write_b32 v150, v98 offset:128
	s_or_b64 exec, exec, s[8:9]
	s_waitcnt lgkmcnt(0)
	v_add_u32_e32 v112, v139, v136
	ds_read_b128 v[100:103], v112 offset:224
	ds_read_b128 v[104:107], v112 offset:192
	ds_read_b128 v[108:111], v112 offset:160
	ds_read_b128 v[112:115], v112 offset:128
	s_waitcnt lgkmcnt(3)
	v_pk_mul_f32 v[12:13], v[12:13], v[100:101]
	s_waitcnt lgkmcnt(2)
	v_pk_mul_f32 v[8:9], v[8:9], v[104:105]
	s_waitcnt lgkmcnt(1)
	v_pk_mul_f32 v[4:5], v[4:5], v[108:109]
	v_pk_mul_f32 v[14:15], v[14:15], v[102:103]
	v_pk_mul_f32 v[10:11], v[10:11], v[106:107]
	v_pk_mul_f32 v[6:7], v[6:7], v[110:111]
	s_waitcnt lgkmcnt(0)
	v_pk_mul_f32 v[2:3], v[2:3], v[114:115]
	v_pk_mul_f32 v[0:1], v[0:1], v[112:113]
	v_pk_mul_f32 v[60:61], v[60:61], v[100:101]
	v_pk_mul_f32 v[56:57], v[56:57], v[104:105]
	v_pk_mul_f32 v[52:53], v[52:53], v[108:109]
	v_pk_mul_f32 v[62:63], v[62:63], v[102:103]
	v_pk_mul_f32 v[58:59], v[58:59], v[106:107]
	v_pk_mul_f32 v[54:55], v[54:55], v[110:111]
	v_pk_mul_f32 v[50:51], v[50:51], v[114:115]
	v_pk_mul_f32 v[48:49], v[48:49], v[112:113]
	v_pk_mul_f32 v[44:45], v[44:45], v[100:101]
	v_pk_mul_f32 v[40:41], v[40:41], v[104:105]
	v_pk_mul_f32 v[36:37], v[36:37], v[108:109]
	v_pk_mul_f32 v[46:47], v[46:47], v[102:103]
	v_pk_mul_f32 v[42:43], v[42:43], v[106:107]
	v_pk_mul_f32 v[38:39], v[38:39], v[110:111]
	v_pk_mul_f32 v[34:35], v[34:35], v[114:115]
	v_pk_mul_f32 v[32:33], v[32:33], v[112:113]
	v_pk_mul_f32 v[28:29], v[28:29], v[100:101]
	v_pk_mul_f32 v[24:25], v[24:25], v[104:105]
	v_pk_mul_f32 v[20:21], v[20:21], v[108:109]
	v_pk_mul_f32 v[30:31], v[30:31], v[102:103]
	v_pk_mul_f32 v[26:27], v[26:27], v[106:107]
	v_pk_mul_f32 v[22:23], v[22:23], v[110:111]
	v_pk_mul_f32 v[18:19], v[18:19], v[114:115]
	v_pk_mul_f32 v[16:17], v[16:17], v[112:113]

; DEV void scan_job(const P& p, int job, char* shm) {
;     ...
;   if (is_prep) PREP(0);
;   __syncthreads();
;   if (is_scan) __builtin_amdgcn_s_setprio(3);
; #pragma unroll 1
;   for (int c = 0; c < nch; ++c) {
;     const int rowbase = s0 + (d ? (nch - 1 - c) : c) * TC;
;     float* Yy = ybase + (c & 1) * ASZ;
;     if (is_scan) {
;       const float* base = lbase + (c & 1) * (6 * ASZ) + np * 8;
;       const float* vbase = lbase + (c & 1) * (6 * ASZ) + 5 * ASZ + 2 * rp;
;       const int tstep = d ? -SLD : SLD;
;       int toff = d ? (TC - 1) * SLD : 0;
;     ...
;       f32x4 Aw0, Aw1, Aq0, Aq1, Ab0, Ab1, Ad0, Ad1, Ar0, Ar1; f32x2 Avv;
;       f32x4 Bw0, Bw1, Bq0, Bq1, Bb0, Bb1, Bd0, Bd1, Br0, Br1; f32x2 Bvv;
;       float yk0 = 0.f, yk1 = 0.f;
.LBB0_1490:
	s_or_b64 exec, exec, s[8:9]
	v_cmp_lt_i32_e64 s[6:7], 3, v42
	v_cmp_gt_i32_e64 s[8:9], 4, v42
	s_waitcnt lgkmcnt(0)
	s_barrier
	s_and_saveexec_b64 s[10:11], s[8:9]
	s_setprio 3
	s_or_b64 exec, exec, s[10:11]
	s_mov_b32 s1, 0x9300000
	s_and_b64 s[10:11], s[30:31], exec
	s_cselect_b32 s1, s1, 0x13300000
	s_add_u32 s16, s82, s1
	s_mov_b32 s35, 0
	s_addc_u32 s17, s83, 0
	s_movk_i32 s1, 0x44
	s_and_b64 s[10:11], s[30:31], exec
	s_mov_b32 s13, s35
	s_cselect_b32 s40, s1, 0xffffffbc
	s_cselect_b32 s41, 0, 0x83c
	s_add_i32 s48, s3, -2
	s_lshl_b32 s34, s12, 6
	s_lshl_b64 s[12:13], s[12:13], 2
	v_bfe_u32 v0, v40, 3, 5
	s_add_u32 s36, s14, s12
	s_addc_u32 s37, s15, s13
	v_or_b32_e32 v143, s0, v0
	s_lshl_b64 s[0:1], s[34:35], 1
	s_add_u32 s12, s16, s0
	v_mov_b32_e32 v89, 0
	v_and_b32_e32 v1, 7, v40
	v_mul_u32_u24_e32 v2, 0x44, v43
	s_addc_u32 s13, s17, s1
	v_mov_b32_e32 v81, v89
	v_lshlrev_b32_e32 v88, 4, v1
	v_lshl_add_u64 v[84:85], s[28:29], 0, v[80:81]
	v_lshl_add_u32 v81, v2, 2, v80
	v_lshrrev_b32_e32 v2, 1, v40
	s_add_u32 s0, s82, s0
	v_lshl_add_u64 v[82:83], s[12:13], 0, v[88:89]
	v_and_b32_e32 v88, 24, v2
	s_addc_u32 s1, s83, s1
	v_lshlrev_b32_e32 v141, 1, v0
	v_mul_i32_i24_e32 v3, s40, v1
	v_mul_u32_u24_e32 v142, 0x110, v0
	v_lshl_add_u64 v[86:87], s[0:1], 0, v[88:89]
	v_lshlrev_b32_e32 v0, 3, v0
	s_lshl_b32 s1, s41, 2
	v_add_u32_e32 v2, s1, v0
	v_lshlrev_b32_e32 v3, 2, v3
	s_mov_b32 s28, 0x19800
	s_add_i32 s41, s41, s40
	v_add3_u32 v145, v2, v3, s28
	s_lshl_b32 s28, s41, 2
	v_add_u32_e32 v0, s28, v0
	v_add_u32_e32 v147, 0xaa00, v0
	v_add_u32_e32 v0, s40, v1
	v_mbcnt_hi_u32_b32 v152, -1, v165
	v_lshlrev_b32_e32 v140, 5, v1
	v_lshlrev_b32_e32 v4, 3, v1
	v_lshl_add_u32 v148, v0, 5, s1
	s_lshl_b32 s49, s40, 2
	v_and_b32_e32 v0, 64, v152
	v_cmp_gt_u32_e64 s[10:11], 16, v41
	v_cmp_eq_u32_e64 s[12:13], 0, v1
	v_cmp_eq_u32_e64 s[14:15], 1, v1
	v_cmp_eq_u32_e64 s[16:17], 2, v1
	v_cmp_eq_u32_e64 s[18:19], 3, v1
	v_cmp_eq_u32_e64 s[20:21], 4, v1
	v_cmp_eq_u32_e64 s[22:23], 5, v1
	v_cmp_eq_u32_e64 s[24:25], 6, v1
	v_cmp_eq_u32_e64 s[26:27], 7, v1
	s_nop 3
	s_or_b64 s[98:99], s[16:17], s[18:19]
	s_or_b64 s[98:99], s[98:99], s[24:25]
	s_or_b64 s[98:99], s[98:99], s[26:27]
	s_or_b64 s[100:101], s[14:15], s[18:19]
	s_or_b64 s[100:101], s[100:101], s[22:23]
	s_or_b64 s[100:101], s[100:101], s[26:27]
	s_movk_i32 s0, 0x2200
	v_add_u32_e32 v144, 0x2200, v81
	s_lshl_b32 s34, s40, 5
	v_add_u32_e32 v146, 0xaa00, v2
	v_add_u32_e32 v149, s28, v140
	s_add_i32 s50, s49, 0x8810
	s_mov_b64 s[42:43], 0
	s_mov_b32 s51, 0xcc00
	s_movk_i32 s54, 0x600
	s_movk_i32 s55, 0x3000
	s_mov_b32 s62, 0xf800000
	v_mov_b32_e32 v150, 0x260
	v_lshlrev_b32_e32 v151, 2, v4
	v_xor_b32_e32 v153, 16, v152
	v_add_u32_e32 v154, 64, v0
	v_xor_b32_e32 v155, 32, v152
	v_mov_b32_e32 v88, v89
	v_mov_b32_e32 v92, v89
	v_mov_b32_e32 v93, v89
	v_mov_b32_e32 v94, v89
	v_mov_b32_e32 v95, v89
	v_mov_b32_e32 v96, v89
	v_mov_b32_e32 v97, v89
	v_mov_b32_e32 v52, v89
	v_mov_b32_e32 v53, v89
	v_mov_b32_e32 v54, v89
	v_mov_b32_e32 v55, v89
	v_mov_b32_e32 v40, v89
	v_mov_b32_e32 v41, v89
	v_mov_b32_e32 v42, v89
	v_mov_b32_e32 v43, v89
	s_branch .LBB0_1494

; #define SBAR() __builtin_amdgcn_sched_barrier(0)
; #define STEP(X, ii) do { ROWSTEP(X, S0, X##vv[0], yk0, ii); ROWSTEP(X, S1, X##vv[1], yk1, ii); } while (0)
; DEV void scan_job(const P& p, int job, char* shm) {
;     ...
;       f32x4 Aw0, Aw1, Aq0, Aq1, Ab0, Ab1, Ad0, Ad1, Ar0, Ar1; f32x2 Avv;
;       f32x4 Bw0, Bw1, Bq0, Bq1, Bb0, Bb1, Bd0, Bd1, Br0, Br1; f32x2 Bvv;
;       float yk0 = 0.f, yk1 = 0.f;
;       LOADOPS(A, toff);
; #pragma unroll 1
;       for (int i = 0; i < TC; i += 8) {
;         const int t8 = toff;
; #pragma unroll
;         for (int u = 0; u < 8; u += 2) {
;           toff += tstep; LOADOPS(B, toff); SBAR();
;           STEP(A, u); SBAR();
;           toff += tstep; if (i + u + 2 < TC) LOADOPS(A, toff);
;           SBAR();
;           STEP(B, u + 1); SBAR();
;         }
;         *reinterpret_cast<f32x2*>(Yy + t8 + np * tstep + 2 * rp) = f32x2{yk0, yk1};
.LBB0_1506:
	s_nop 0
	v_add_f32_dpp v176, v88, v88 row_half_mirror row_mask:0xf bank_mask:0x5 bound_ctrl:1
	v_add_f32_dpp v177, v89, v89 row_half_mirror row_mask:0xf bank_mask:0x5 bound_ctrl:1
	v_add_f32_dpp v178, v94, v94 row_half_mirror row_mask:0xf bank_mask:0x5 bound_ctrl:1
	v_add_f32_dpp v179, v95, v95 row_half_mirror row_mask:0xf bank_mask:0x5 bound_ctrl:1
	v_add_f32_dpp v180, v100, v100 row_half_mirror row_mask:0xf bank_mask:0x5 bound_ctrl:1
	v_add_f32_dpp v181, v101, v101 row_half_mirror row_mask:0xf bank_mask:0x5 bound_ctrl:1
	v_add_f32_dpp v176, v126, v126 row_half_mirror row_mask:0xf bank_mask:0xa bound_ctrl:1
	v_add_f32_dpp v177, v127, v127 row_half_mirror row_mask:0xf bank_mask:0xa bound_ctrl:1
	v_add_f32_dpp v178, v130, v130 row_half_mirror row_mask:0xf bank_mask:0xa bound_ctrl:1
	v_add_f32_dpp v179, v131, v131 row_half_mirror row_mask:0xf bank_mask:0xa bound_ctrl:1
	v_add_f32_dpp v180, v134, v134 row_half_mirror row_mask:0xf bank_mask:0xa bound_ctrl:1
	v_add_f32_dpp v181, v135, v135 row_half_mirror row_mask:0xf bank_mask:0xa bound_ctrl:1
	s_waitcnt lgkmcnt(8)
	v_pk_mul_f32 v[88:89], v[76:77], v[110:111]
	v_pk_mul_f32 v[90:91], v[78:79], v[112:113]
	v_pk_mul_f32 v[76:77], v[76:77], v[118:119]
	v_pk_mul_f32 v[78:79], v[78:79], v[120:121]
	s_waitcnt lgkmcnt(7)
	v_pk_fma_f32 v[88:89], v[72:73], v[114:115], v[88:89]
	v_pk_fma_f32 v[90:91], v[74:75], v[116:117], v[90:91]
	v_pk_fma_f32 v[72:73], v[72:73], v[122:123], v[76:77]
	v_pk_fma_f32 v[74:75], v[74:75], v[124:125], v[78:79]
	v_pk_add_f32 v[88:89], v[88:89], v[90:91]
	v_pk_add_f32 v[72:73], v[72:73], v[74:75]
	v_add_f32_e32 v88, v88, v89
	v_add_f32_e32 v72, v72, v73
	s_nop 0
	v_add_f32_dpp v88, v88, v88 quad_perm:[1,0,3,2] row_mask:0xf bank_mask:0xf bound_ctrl:1
	v_add_f32_dpp v72, v72, v72 quad_perm:[1,0,3,2] row_mask:0xf bank_mask:0xf bound_ctrl:1
	s_nop 0
	v_add_f32_dpp v88, v88, v88 quad_perm:[2,3,0,1] row_mask:0xf bank_mask:0xf bound_ctrl:1
	v_add_f32_dpp v72, v72, v72 quad_perm:[2,3,0,1] row_mask:0xf bank_mask:0xf bound_ctrl:1
	s_nop 0
	v_add_f32_dpp v90, v88, v88 row_half_mirror row_mask:0xf bank_mask:0xf bound_ctrl:1
	v_add_f32_dpp v72, v72, v72 row_half_mirror row_mask:0xf bank_mask:0xf bound_ctrl:1
	s_waitcnt lgkmcnt(6)
	v_pk_mul_f32 v[88:89], v[64:65], v[90:91] op_sel_hi:[1,0] neg_lo:[0,1] neg_hi:[0,1]
	v_pk_mul_f32 v[64:65], v[64:65], v[72:73] op_sel_hi:[1,0] neg_lo:[0,1] neg_hi:[0,1]
	v_pk_fma_f32 v[88:89], v[52:53], v[110:111], v[88:89]
	v_pk_mul_f32 v[92:93], v[66:67], v[90:91] op_sel_hi:[1,0] neg_lo:[0,1] neg_hi:[0,1]
	s_waitcnt lgkmcnt(5)
	v_pk_mul_f32 v[94:95], v[56:57], v[90:91] op_sel_hi:[1,0] neg_lo:[0,1] neg_hi:[0,1]
	v_pk_fma_f32 v[52:53], v[52:53], v[118:119], v[64:65]
	v_pk_mul_f32 v[64:65], v[66:67], v[72:73] op_sel_hi:[1,0] neg_lo:[0,1] neg_hi:[0,1]
	v_pk_mul_f32 v[56:57], v[56:57], v[72:73] op_sel_hi:[1,0] neg_lo:[0,1] neg_hi:[0,1]
	v_pk_fma_f32 v[92:93], v[54:55], v[112:113], v[92:93]
	v_pk_fma_f32 v[94:95], v[40:41], v[114:115], v[94:95]
	v_pk_mul_f32 v[90:91], v[58:59], v[90:91] op_sel_hi:[1,0] neg_lo:[0,1] neg_hi:[0,1]
	v_pk_fma_f32 v[54:55], v[54:55], v[120:121], v[64:65]
	v_pk_fma_f32 v[40:41], v[40:41], v[122:123], v[56:57]
	v_pk_mul_f32 v[56:57], v[58:59], v[72:73] op_sel_hi:[1,0] neg_lo:[0,1] neg_hi:[0,1]
	s_waitcnt lgkmcnt(0)
	v_pk_fma_f32 v[88:89], v[68:69], v[104:105], v[88:89] op_sel_hi:[1,0,1]
	v_pk_fma_f32 v[92:93], v[70:71], v[104:105], v[92:93] op_sel_hi:[1,0,1]
	v_pk_fma_f32 v[90:91], v[42:43], v[116:117], v[90:91]
	v_pk_fma_f32 v[52:53], v[68:69], v[104:105], v[52:53] op_sel:[0,1,0]
	v_pk_fma_f32 v[54:55], v[70:71], v[104:105], v[54:55] op_sel:[0,1,0]
	v_pk_fma_f32 v[42:43], v[42:43], v[124:125], v[56:57]
	v_pk_fma_f32 v[94:95], v[60:61], v[104:105], v[94:95] op_sel_hi:[1,0,1]
	v_pk_fma_f32 v[96:97], v[62:63], v[104:105], v[90:91] op_sel_hi:[1,0,1]
	v_pk_mul_f32 v[90:91], v[48:49], v[88:89]
	v_pk_mul_f32 v[100:101], v[50:51], v[92:93]
	v_pk_fma_f32 v[40:41], v[60:61], v[104:105], v[40:41] op_sel:[0,1,0]
	v_pk_fma_f32 v[42:43], v[62:63], v[104:105], v[42:43] op_sel:[0,1,0]
	v_pk_mul_f32 v[48:49], v[48:49], v[52:53]
	v_pk_mul_f32 v[50:51], v[50:51], v[54:55]
	v_pk_fma_f32 v[90:91], v[44:45], v[94:95], v[90:91]
	v_pk_fma_f32 v[100:101], v[46:47], v[96:97], v[100:101]
	v_pk_fma_f32 v[44:45], v[44:45], v[40:41], v[48:49]
	v_pk_fma_f32 v[46:47], v[46:47], v[42:43], v[50:51]
	v_pk_add_f32 v[90:91], v[90:91], v[100:101]
	v_pk_add_f32 v[44:45], v[44:45], v[46:47]
	v_mov_b32_e32 v46, v90
	v_mov_b32_e32 v47, v44
	v_mov_b32_e32 v44, v91
	v_pk_add_f32 v[44:45], v[46:47], v[44:45]
	s_nop 1
	v_add_f32_dpp v182, v106, v106 row_half_mirror row_mask:0xf bank_mask:0x5 bound_ctrl:1
	v_add_f32_dpp v183, v107, v107 row_half_mirror row_mask:0xf bank_mask:0x5 bound_ctrl:1
	v_add_f32_dpp v182, v44, v44 row_half_mirror row_mask:0xf bank_mask:0xa bound_ctrl:1
	v_add_f32_dpp v183, v45, v45 row_half_mirror row_mask:0xf bank_mask:0xa bound_ctrl:1
	v_add_f32_dpp v176, v176, v176 quad_perm:[2,3,0,1] row_mask:0xf bank_mask:0xf bound_ctrl:1
	v_add_f32_dpp v177, v177, v177 quad_perm:[2,3,0,1] row_mask:0xf bank_mask:0xf bound_ctrl:1
	v_add_f32_dpp v178, v178, v178 quad_perm:[2,3,0,1] row_mask:0xf bank_mask:0xf bound_ctrl:1
	v_add_f32_dpp v179, v179, v179 quad_perm:[2,3,0,1] row_mask:0xf bank_mask:0xf bound_ctrl:1
	v_add_f32_dpp v180, v180, v180 quad_perm:[2,3,0,1] row_mask:0xf bank_mask:0xf bound_ctrl:1
	v_add_f32_dpp v181, v181, v181 quad_perm:[2,3,0,1] row_mask:0xf bank_mask:0xf bound_ctrl:1
	v_add_f32_dpp v182, v182, v182 quad_perm:[2,3,0,1] row_mask:0xf bank_mask:0xf bound_ctrl:1
	v_add_f32_dpp v183, v183, v183 quad_perm:[2,3,0,1] row_mask:0xf bank_mask:0xf bound_ctrl:1
	v_cndmask_b32_e64 v176, v176, v180, s[98:99]
	v_cndmask_b32_e64 v177, v177, v181, s[98:99]
	v_cndmask_b32_e64 v178, v178, v182, s[98:99]
	v_cndmask_b32_e64 v179, v179, v183, s[98:99]
	v_add_f32_dpp v176, v176, v176 quad_perm:[1,0,3,2] row_mask:0xf bank_mask:0xf bound_ctrl:1
	v_add_f32_dpp v177, v177, v177 quad_perm:[1,0,3,2] row_mask:0xf bank_mask:0xf bound_ctrl:1
	v_add_f32_dpp v178, v178, v178 quad_perm:[1,0,3,2] row_mask:0xf bank_mask:0xf bound_ctrl:1
	v_add_f32_dpp v179, v179, v179 quad_perm:[1,0,3,2] row_mask:0xf bank_mask:0xf bound_ctrl:1
	v_cndmask_b32_e64 v90, v176, v178, s[100:101]
	v_cndmask_b32_e64 v91, v177, v179, s[100:101]
	s_add_i32 s45, s45, 8
	ds_write_b64 v156, v[90:91]
	v_add_u32_e32 v156, s34, v156
	v_add_u32_e32 v157, s34, v157
	v_add_u32_e32 v158, s34, v158
	v_add_u32_e32 v159, s34, v159
	s_cmp_gt_u32 s45, 23
	v_add_u32_e32 v160, s34, v160
	s_cbranch_scc1 .LBB0_1509
; #define SBAR() __builtin_amdgcn_sched_barrier(0)
; #define STEP(X, ii) do { ROWSTEP(X, S0, X##vv[0], yk0, ii); ROWSTEP(X, S1, X##vv[1], yk1, ii); } while (0)
; DEV void scan_job(const P& p, int job, char* shm) {
;     ...
;       f32x4 Aw0, Aw1, Aq0, Aq1, Ab0, Ab1, Ad0, Ad1, Ar0, Ar1; f32x2 Avv;
;       f32x4 Bw0, Bw1, Bq0, Bq1, Bb0, Bb1, Bd0, Bd1, Br0, Br1; f32x2 Bvv;
;       float yk0 = 0.f, yk1 = 0.f;
;       LOADOPS(A, toff);
; #pragma unroll 1
;       for (int i = 0; i < TC; i += 8) {
;         const int t8 = toff;
; #pragma unroll
;         for (int u = 0; u < 8; u += 2) {
;           toff += tstep; LOADOPS(B, toff); SBAR();
;           STEP(A, u); SBAR();
;           toff += tstep; if (i + u + 2 < TC) LOADOPS(A, toff);
;           SBAR();
;           STEP(B, u + 1); SBAR();
.LBB0_1507:
	ds_read_b128 v[44:47], v160
	ds_read_b128 v[48:51], v160 offset:16
	ds_read_b128 v[56:59], v160 offset:8704
	ds_read_b128 v[60:63], v160 offset:8720
	ds_read_b128 v[64:67], v160 offset:17408
	ds_read_b128 v[68:71], v160 offset:17424
	ds_read_b128 v[72:75], v160 offset:26112
	ds_read_b128 v[76:79], v160 offset:26128
	ds_read_b128 v[100:103], v160 offset:34816
	ds_read_b128 v[104:107], v160 offset:34832
	ds_read_b64 v[108:109], v158
	s_waitcnt lgkmcnt(14)
	v_pk_mul_f32 v[110:111], v[36:37], v[88:89]
	v_pk_mul_f32 v[112:113], v[38:39], v[92:93]
	v_pk_fma_f32 v[110:111], v[32:33], v[94:95], v[110:111]
	v_pk_fma_f32 v[112:113], v[34:35], v[96:97], v[112:113]
	v_pk_mul_f32 v[36:37], v[36:37], v[52:53]
	v_pk_add_f32 v[110:111], v[110:111], v[112:113]
	v_pk_mul_f32 v[38:39], v[38:39], v[54:55]
	v_add_f32_e32 v110, v110, v111
	v_pk_fma_f32 v[32:33], v[32:33], v[40:41], v[36:37]
	v_pk_fma_f32 v[34:35], v[34:35], v[42:43], v[38:39]
	v_add_f32_dpp v110, v110, v110 quad_perm:[1,0,3,2] row_mask:0xf bank_mask:0xf bound_ctrl:1
	v_pk_add_f32 v[32:33], v[32:33], v[34:35]
	s_nop 0
	v_add_f32_dpp v110, v110, v110 quad_perm:[2,3,0,1] row_mask:0xf bank_mask:0xf bound_ctrl:1
	v_add_f32_e32 v32, v32, v33
	s_nop 0
	v_add_f32_dpp v110, v110, v110 row_half_mirror row_mask:0xf bank_mask:0xf bound_ctrl:1
	v_pk_mul_f32 v[112:113], v[24:25], v[110:111] op_sel_hi:[1,0] neg_lo:[0,1] neg_hi:[0,1]
	v_add_f32_dpp v32, v32, v32 quad_perm:[1,0,3,2] row_mask:0xf bank_mask:0xf bound_ctrl:1
	v_pk_fma_f32 v[88:89], v[28:29], v[88:89], v[112:113]
	s_nop 0
	v_add_f32_dpp v32, v32, v32 quad_perm:[2,3,0,1] row_mask:0xf bank_mask:0xf bound_ctrl:1
	s_waitcnt lgkmcnt(11)
	v_pk_fma_f32 v[112:113], v[20:21], v[98:99], v[88:89] op_sel_hi:[1,0,1]
	v_pk_mul_f32 v[88:89], v[26:27], v[110:111] op_sel_hi:[1,0] neg_lo:[0,1] neg_hi:[0,1]
	v_add_f32_dpp v32, v32, v32 row_half_mirror row_mask:0xf bank_mask:0xf bound_ctrl:1
	v_pk_fma_f32 v[88:89], v[30:31], v[92:93], v[88:89]
	v_pk_mul_f32 v[24:25], v[24:25], v[32:33] op_sel_hi:[1,0] neg_lo:[0,1] neg_hi:[0,1]
	v_pk_fma_f32 v[114:115], v[22:23], v[98:99], v[88:89] op_sel_hi:[1,0,1]
	v_pk_mul_f32 v[88:89], v[8:9], v[110:111] op_sel_hi:[1,0] neg_lo:[0,1] neg_hi:[0,1]
	v_pk_fma_f32 v[24:25], v[28:29], v[52:53], v[24:25]
	v_pk_mul_f32 v[8:9], v[8:9], v[32:33] op_sel_hi:[1,0] neg_lo:[0,1] neg_hi:[0,1]
	v_pk_fma_f32 v[88:89], v[0:1], v[94:95], v[88:89]
	v_pk_fma_f32 v[52:53], v[20:21], v[98:99], v[24:25] op_sel:[0,1,0]
	v_pk_mul_f32 v[20:21], v[26:27], v[32:33] op_sel_hi:[1,0] neg_lo:[0,1] neg_hi:[0,1]
	v_pk_fma_f32 v[0:1], v[0:1], v[40:41], v[8:9]
	v_pk_fma_f32 v[94:95], v[12:13], v[98:99], v[88:89] op_sel_hi:[1,0,1]
	v_pk_mul_f32 v[88:89], v[10:11], v[110:111] op_sel_hi:[1,0] neg_lo:[0,1] neg_hi:[0,1]
	v_pk_fma_f32 v[20:21], v[30:31], v[54:55], v[20:21]
	v_pk_fma_f32 v[40:41], v[12:13], v[98:99], v[0:1] op_sel:[0,1,0]
	v_pk_mul_f32 v[0:1], v[10:11], v[32:33] op_sel_hi:[1,0] neg_lo:[0,1] neg_hi:[0,1]
	v_pk_fma_f32 v[88:89], v[2:3], v[96:97], v[88:89]
	v_pk_fma_f32 v[54:55], v[22:23], v[98:99], v[20:21] op_sel:[0,1,0]
	v_pk_fma_f32 v[0:1], v[2:3], v[42:43], v[0:1]
	v_pk_fma_f32 v[96:97], v[14:15], v[98:99], v[88:89] op_sel_hi:[1,0,1]
	v_pk_mul_f32 v[88:89], v[16:17], v[112:113]
	v_pk_mul_f32 v[92:93], v[18:19], v[114:115]
	v_pk_fma_f32 v[42:43], v[14:15], v[98:99], v[0:1] op_sel:[0,1,0]
	v_pk_mul_f32 v[0:1], v[16:17], v[52:53]
	v_pk_mul_f32 v[2:3], v[18:19], v[54:55]
	v_pk_fma_f32 v[88:89], v[4:5], v[94:95], v[88:89]
	v_pk_fma_f32 v[92:93], v[6:7], v[96:97], v[92:93]
	v_pk_fma_f32 v[0:1], v[4:5], v[40:41], v[0:1]
	v_pk_fma_f32 v[2:3], v[6:7], v[42:43], v[2:3]
	v_pk_add_f32 v[88:89], v[88:89], v[92:93]
	v_pk_add_f32 v[0:1], v[0:1], v[2:3]
	v_add_f32_e32 v88, v88, v89
	v_add_f32_e32 v89, v0, v1
	s_nop 1
	v_add_u32_e32 v124, s49, v158
	v_add_u32_e32 v125, s49, v160
	ds_read_b64 v[98:99], v124
	ds_read_b128 v[0:3], v125 offset:34816
	ds_read_b128 v[4:7], v125 offset:26128
	ds_read_b128 v[8:11], v125 offset:26112
	ds_read_b128 v[12:15], v125 offset:34832
	ds_read_b128 v[16:19], v125 offset:17424
	ds_read_b128 v[20:23], v125 offset:17408
	ds_read_b128 v[24:27], v125 offset:8720
	ds_read_b128 v[28:31], v125 offset:8704
	ds_read_b128 v[32:35], v125 offset:16
	ds_read_b128 v[36:39], v125
	s_waitcnt lgkmcnt(14)
	v_pk_mul_f32 v[110:111], v[56:57], v[112:113]
	v_pk_mul_f32 v[116:117], v[58:59], v[114:115]
	v_pk_mul_f32 v[56:57], v[56:57], v[52:53]
	v_pk_mul_f32 v[58:59], v[58:59], v[54:55]
	v_pk_fma_f32 v[110:111], v[60:61], v[94:95], v[110:111]
	v_pk_fma_f32 v[116:117], v[62:63], v[96:97], v[116:117]
	v_pk_fma_f32 v[56:57], v[60:61], v[40:41], v[56:57]
	v_pk_fma_f32 v[58:59], v[62:63], v[42:43], v[58:59]
	v_pk_add_f32 v[110:111], v[110:111], v[116:117]
	v_pk_add_f32 v[56:57], v[56:57], v[58:59]
	v_add_f32_e32 v110, v110, v111
	v_add_f32_e32 v56, v56, v57
	s_nop 0
	v_add_f32_dpp v110, v110, v110 quad_perm:[1,0,3,2] row_mask:0xf bank_mask:0xf bound_ctrl:1
	v_add_f32_dpp v56, v56, v56 quad_perm:[1,0,3,2] row_mask:0xf bank_mask:0xf bound_ctrl:1
	s_nop 0
	v_add_f32_dpp v110, v110, v110 quad_perm:[2,3,0,1] row_mask:0xf bank_mask:0xf bound_ctrl:1
	v_add_f32_dpp v56, v56, v56 quad_perm:[2,3,0,1] row_mask:0xf bank_mask:0xf bound_ctrl:1
	s_nop 0
	v_add_f32_dpp v110, v110, v110 row_half_mirror row_mask:0xf bank_mask:0xf bound_ctrl:1
	v_add_f32_dpp v56, v56, v56 row_half_mirror row_mask:0xf bank_mask:0xf bound_ctrl:1
	v_pk_mul_f32 v[116:117], v[64:65], v[110:111] op_sel_hi:[1,0] neg_lo:[0,1] neg_hi:[0,1]
	v_pk_mul_f32 v[58:59], v[64:65], v[56:57] op_sel_hi:[1,0] neg_lo:[0,1] neg_hi:[0,1]
	v_pk_fma_f32 v[112:113], v[44:45], v[112:113], v[116:117]
	v_pk_fma_f32 v[44:45], v[44:45], v[52:53], v[58:59]
	v_pk_mul_f32 v[116:117], v[66:67], v[110:111] op_sel_hi:[1,0] neg_lo:[0,1] neg_hi:[0,1]
	s_waitcnt lgkmcnt(11)
; #define SBAR() __builtin_amdgcn_sched_barrier(0)
; #define STEP(X, ii) do { ROWSTEP(X, S0, X##vv[0], yk0, ii); ROWSTEP(X, S1, X##vv[1], yk1, ii); } while (0)
; DEV void scan_job(const P& p, int job, char* shm) {
;     ...
;       f32x4 Aw0, Aw1, Aq0, Aq1, Ab0, Ab1, Ad0, Ad1, Ar0, Ar1; f32x2 Avv;
;       f32x4 Bw0, Bw1, Bq0, Bq1, Bb0, Bb1, Bd0, Bd1, Br0, Br1; f32x2 Bvv;
;       float yk0 = 0.f, yk1 = 0.f;
;       LOADOPS(A, toff);
; #pragma unroll 1
;       for (int i = 0; i < TC; i += 8) {
;         const int t8 = toff;
; #pragma unroll
;         for (int u = 0; u < 8; u += 2) {
;           toff += tstep; LOADOPS(B, toff); SBAR();
;           STEP(A, u); SBAR();
;           toff += tstep; if (i + u + 2 < TC) LOADOPS(A, toff);
	v_pk_fma_f32 v[118:119], v[72:73], v[108:109], v[44:45] op_sel:[0,1,0]
	v_pk_mul_f32 v[44:45], v[66:67], v[56:57] op_sel_hi:[1,0] neg_lo:[0,1] neg_hi:[0,1]
	v_pk_fma_f32 v[114:115], v[46:47], v[114:115], v[116:117]
	v_pk_fma_f32 v[44:45], v[46:47], v[54:55], v[44:45]
	v_pk_mul_f32 v[116:117], v[68:69], v[110:111] op_sel_hi:[1,0] neg_lo:[0,1] neg_hi:[0,1]
	v_pk_fma_f32 v[120:121], v[74:75], v[108:109], v[44:45] op_sel:[0,1,0]
	v_pk_mul_f32 v[44:45], v[68:69], v[56:57] op_sel_hi:[1,0] neg_lo:[0,1] neg_hi:[0,1]
	v_pk_fma_f32 v[94:95], v[48:49], v[94:95], v[116:117]
	v_pk_fma_f32 v[40:41], v[48:49], v[40:41], v[44:45]
	v_pk_fma_f32 v[116:117], v[76:77], v[108:109], v[94:95] op_sel_hi:[1,0,1]
	v_pk_mul_f32 v[94:95], v[70:71], v[110:111] op_sel_hi:[1,0] neg_lo:[0,1] neg_hi:[0,1]
	v_pk_fma_f32 v[122:123], v[76:77], v[108:109], v[40:41] op_sel:[0,1,0]
	v_pk_mul_f32 v[40:41], v[70:71], v[56:57] op_sel_hi:[1,0] neg_lo:[0,1] neg_hi:[0,1]
	v_pk_fma_f32 v[112:113], v[72:73], v[108:109], v[112:113] op_sel_hi:[1,0,1]
	v_pk_fma_f32 v[114:115], v[74:75], v[108:109], v[114:115] op_sel_hi:[1,0,1]
	v_pk_fma_f32 v[94:95], v[50:51], v[96:97], v[94:95]
	v_pk_fma_f32 v[40:41], v[50:51], v[42:43], v[40:41]
	v_pk_fma_f32 v[110:111], v[78:79], v[108:109], v[94:95] op_sel_hi:[1,0,1]
	v_pk_mul_f32 v[94:95], v[100:101], v[112:113]
	v_pk_mul_f32 v[96:97], v[102:103], v[114:115]
	v_pk_fma_f32 v[108:109], v[78:79], v[108:109], v[40:41] op_sel:[0,1,0]
	v_pk_mul_f32 v[40:41], v[100:101], v[118:119]
	v_pk_mul_f32 v[42:43], v[102:103], v[120:121]
	v_pk_fma_f32 v[94:95], v[104:105], v[116:117], v[94:95]
	v_pk_fma_f32 v[96:97], v[106:107], v[110:111], v[96:97]
	v_pk_fma_f32 v[40:41], v[104:105], v[122:123], v[40:41]
	v_pk_fma_f32 v[42:43], v[106:107], v[108:109], v[42:43]
	v_pk_add_f32 v[94:95], v[94:95], v[96:97]
	v_pk_add_f32 v[96:97], v[40:41], v[42:43]
	v_add_u32_e32 v125, s49, v125
	ds_read_b128 v[40:43], v125
	ds_read_b128 v[44:47], v125 offset:16
	ds_read_b128 v[48:51], v125 offset:8704
	ds_read_b128 v[52:55], v125 offset:8720
	ds_read_b128 v[56:59], v125 offset:17408
	ds_read_b128 v[60:63], v125 offset:17424
	ds_read_b128 v[64:67], v125 offset:26112
	ds_read_b128 v[68:71], v125 offset:26128
	ds_read_b128 v[72:75], v125 offset:34816
	ds_read_b128 v[76:79], v125 offset:34832
	v_add_u32_e32 v124, s49, v124
	ds_read_b64 v[104:105], v124
	s_waitcnt lgkmcnt(13)
	v_pk_mul_f32 v[100:101], v[28:29], v[112:113]
	v_pk_mul_f32 v[102:103], v[30:31], v[114:115]
	v_pk_fma_f32 v[100:101], v[24:25], v[116:117], v[100:101]
	v_pk_fma_f32 v[102:103], v[26:27], v[110:111], v[102:103]
	v_pk_mul_f32 v[28:29], v[28:29], v[118:119]
	v_pk_add_f32 v[100:101], v[100:101], v[102:103]
	v_pk_mul_f32 v[30:31], v[30:31], v[120:121]
	v_add_f32_e32 v100, v100, v101
	v_pk_fma_f32 v[24:25], v[24:25], v[122:123], v[28:29]
	v_pk_fma_f32 v[26:27], v[26:27], v[108:109], v[30:31]
	v_add_f32_dpp v100, v100, v100 quad_perm:[1,0,3,2] row_mask:0xf bank_mask:0xf bound_ctrl:1
	v_pk_add_f32 v[24:25], v[24:25], v[26:27]
	s_nop 0
	v_add_f32_dpp v100, v100, v100 quad_perm:[2,3,0,1] row_mask:0xf bank_mask:0xf bound_ctrl:1
	v_add_f32_e32 v24, v24, v25
	s_nop 0
	v_add_f32_dpp v100, v100, v100 row_half_mirror row_mask:0xf bank_mask:0xf bound_ctrl:1
	v_pk_mul_f32 v[102:103], v[20:21], v[100:101] op_sel_hi:[1,0] neg_lo:[0,1] neg_hi:[0,1]
	v_add_f32_dpp v24, v24, v24 quad_perm:[1,0,3,2] row_mask:0xf bank_mask:0xf bound_ctrl:1
	s_waitcnt lgkmcnt(11)
	v_pk_fma_f32 v[102:103], v[36:37], v[112:113], v[102:103]
	v_add_f32_dpp v24, v24, v24 quad_perm:[2,3,0,1] row_mask:0xf bank_mask:0xf bound_ctrl:1
	v_pk_fma_f32 v[106:107], v[98:99], v[8:9], v[102:103] op_sel_hi:[0,1,1]
	v_pk_mul_f32 v[102:103], v[22:23], v[100:101] op_sel_hi:[1,0] neg_lo:[0,1] neg_hi:[0,1]
	v_add_f32_dpp v24, v24, v24 row_half_mirror row_mask:0xf bank_mask:0xf bound_ctrl:1
	v_pk_fma_f32 v[102:103], v[38:39], v[114:115], v[102:103]
	v_pk_mul_f32 v[20:21], v[20:21], v[24:25] op_sel_hi:[1,0] neg_lo:[0,1] neg_hi:[0,1]
	v_pk_fma_f32 v[112:113], v[98:99], v[10:11], v[102:103] op_sel_hi:[0,1,1]
	v_pk_mul_f32 v[102:103], v[16:17], v[100:101] op_sel_hi:[1,0] neg_lo:[0,1] neg_hi:[0,1]
	v_pk_fma_f32 v[20:21], v[36:37], v[118:119], v[20:21]
	v_pk_fma_f32 v[102:103], v[32:33], v[116:117], v[102:103]
	v_pk_fma_f32 v[116:117], v[98:99], v[8:9], v[20:21] op_sel:[1,0,0]
	v_pk_mul_f32 v[8:9], v[22:23], v[24:25] op_sel_hi:[1,0] neg_lo:[0,1] neg_hi:[0,1]
	v_pk_fma_f32 v[114:115], v[98:99], v[4:5], v[102:103] op_sel_hi:[0,1,1]
	v_pk_fma_f32 v[8:9], v[38:39], v[120:121], v[8:9]
	v_pk_mul_f32 v[100:101], v[18:19], v[100:101] op_sel_hi:[1,0] neg_lo:[0,1] neg_hi:[0,1]
	v_pk_fma_f32 v[118:119], v[98:99], v[10:11], v[8:9] op_sel:[1,0,0]
	v_pk_mul_f32 v[8:9], v[16:17], v[24:25] op_sel_hi:[1,0] neg_lo:[0,1] neg_hi:[0,1]
	v_pk_fma_f32 v[100:101], v[34:35], v[110:111], v[100:101]
	v_pk_fma_f32 v[8:9], v[32:33], v[122:123], v[8:9]
	v_pk_fma_f32 v[110:111], v[98:99], v[6:7], v[100:101] op_sel_hi:[0,1,1]
	v_pk_fma_f32 v[120:121], v[98:99], v[4:5], v[8:9] op_sel:[1,0,0]
	v_pk_mul_f32 v[4:5], v[18:19], v[24:25] op_sel_hi:[1,0] neg_lo:[0,1] neg_hi:[0,1]
	v_pk_mul_f32 v[100:101], v[0:1], v[106:107]
	v_pk_fma_f32 v[4:5], v[34:35], v[108:109], v[4:5]
	v_pk_mul_f32 v[102:103], v[2:3], v[112:113]
	v_pk_fma_f32 v[98:99], v[98:99], v[6:7], v[4:5] op_sel:[1,0,0]
	v_pk_mul_f32 v[0:1], v[0:1], v[116:117]
	v_pk_mul_f32 v[2:3], v[2:3], v[118:119]
	v_pk_fma_f32 v[100:101], v[12:13], v[114:115], v[100:101]
	v_pk_fma_f32 v[102:103], v[14:15], v[110:111], v[102:103]
	v_pk_fma_f32 v[0:1], v[12:13], v[120:121], v[0:1]
	v_pk_fma_f32 v[2:3], v[14:15], v[98:99], v[2:3]
	v_pk_add_f32 v[100:101], v[100:101], v[102:103]
	v_pk_add_f32 v[102:103], v[0:1], v[2:3]
	v_add_u32_e32 v126, s49, v124
	v_add_u32_e32 v127, s49, v125
	ds_read_b64 v[122:123], v126
	ds_read_b128 v[0:3], v127 offset:34832
	ds_read_b128 v[4:7], v127 offset:34816
	ds_read_b128 v[8:11], v127 offset:26128
	ds_read_b128 v[12:15], v127 offset:26112
	ds_read_b128 v[16:19], v127 offset:17424
	ds_read_b128 v[20:23], v127 offset:17408
	ds_read_b128 v[24:27], v127 offset:8720
	ds_read_b128 v[28:31], v127 offset:8704
	ds_read_b128 v[32:35], v127 offset:16
	ds_read_b128 v[36:39], v127
	s_waitcnt lgkmcnt(14)
; #define SBAR() __builtin_amdgcn_sched_barrier(0)
; #define STEP(X, ii) do { ROWSTEP(X, S0, X##vv[0], yk0, ii); ROWSTEP(X, S1, X##vv[1], yk1, ii); } while (0)
; DEV void scan_job(const P& p, int job, char* shm) {
;     ...
;       f32x4 Aw0, Aw1, Aq0, Aq1, Ab0, Ab1, Ad0, Ad1, Ar0, Ar1; f32x2 Avv;
;       f32x4 Bw0, Bw1, Bq0, Bq1, Bb0, Bb1, Bd0, Bd1, Br0, Br1; f32x2 Bvv;
;       float yk0 = 0.f, yk1 = 0.f;
;       LOADOPS(A, toff);
; #pragma unroll 1
;       for (int i = 0; i < TC; i += 8) {
;         const int t8 = toff;
; #pragma unroll
;         for (int u = 0; u < 8; u += 2) {
;           toff += tstep; LOADOPS(B, toff); SBAR();
;           STEP(A, u); SBAR();
;           toff += tstep; if (i + u + 2 < TC) LOADOPS(A, toff);
	v_pk_mul_f32 v[108:109], v[48:49], v[106:107]
	v_pk_mul_f32 v[124:125], v[50:51], v[112:113]
	v_pk_mul_f32 v[48:49], v[48:49], v[116:117]
	v_pk_mul_f32 v[50:51], v[50:51], v[118:119]
	v_pk_fma_f32 v[108:109], v[52:53], v[114:115], v[108:109]
	v_pk_fma_f32 v[124:125], v[54:55], v[110:111], v[124:125]
	v_pk_fma_f32 v[48:49], v[52:53], v[120:121], v[48:49]
	v_pk_fma_f32 v[50:51], v[54:55], v[98:99], v[50:51]
	v_pk_add_f32 v[108:109], v[108:109], v[124:125]
	v_pk_add_f32 v[48:49], v[48:49], v[50:51]
	v_add_f32_e32 v108, v108, v109
	v_add_f32_e32 v48, v48, v49
	s_nop 0
	v_add_f32_dpp v108, v108, v108 quad_perm:[1,0,3,2] row_mask:0xf bank_mask:0xf bound_ctrl:1
	v_add_f32_dpp v48, v48, v48 quad_perm:[1,0,3,2] row_mask:0xf bank_mask:0xf bound_ctrl:1
	s_nop 0
	v_add_f32_dpp v108, v108, v108 quad_perm:[2,3,0,1] row_mask:0xf bank_mask:0xf bound_ctrl:1
	v_add_f32_dpp v48, v48, v48 quad_perm:[2,3,0,1] row_mask:0xf bank_mask:0xf bound_ctrl:1
	s_nop 0
	v_add_f32_dpp v108, v108, v108 row_half_mirror row_mask:0xf bank_mask:0xf bound_ctrl:1
	v_add_f32_dpp v48, v48, v48 row_half_mirror row_mask:0xf bank_mask:0xf bound_ctrl:1
	v_pk_mul_f32 v[124:125], v[56:57], v[108:109] op_sel_hi:[1,0] neg_lo:[0,1] neg_hi:[0,1]
	v_pk_mul_f32 v[50:51], v[56:57], v[48:49] op_sel_hi:[1,0] neg_lo:[0,1] neg_hi:[0,1]
	v_pk_fma_f32 v[106:107], v[40:41], v[106:107], v[124:125]
	v_pk_fma_f32 v[40:41], v[40:41], v[116:117], v[50:51]
	s_waitcnt lgkmcnt(11)
	v_pk_fma_f32 v[124:125], v[64:65], v[104:105], v[106:107] op_sel_hi:[1,0,1]
	v_pk_mul_f32 v[106:107], v[58:59], v[108:109] op_sel_hi:[1,0] neg_lo:[0,1] neg_hi:[0,1]
	v_pk_fma_f32 v[116:117], v[64:65], v[104:105], v[40:41] op_sel:[0,1,0]
	v_pk_mul_f32 v[40:41], v[58:59], v[48:49] op_sel_hi:[1,0] neg_lo:[0,1] neg_hi:[0,1]
	v_pk_fma_f32 v[106:107], v[42:43], v[112:113], v[106:107]
	v_pk_fma_f32 v[40:41], v[42:43], v[118:119], v[40:41]
	v_pk_fma_f32 v[112:113], v[66:67], v[104:105], v[106:107] op_sel_hi:[1,0,1]
	v_pk_mul_f32 v[106:107], v[60:61], v[108:109] op_sel_hi:[1,0] neg_lo:[0,1] neg_hi:[0,1]
	v_pk_fma_f32 v[118:119], v[66:67], v[104:105], v[40:41] op_sel:[0,1,0]
	v_pk_mul_f32 v[40:41], v[60:61], v[48:49] op_sel_hi:[1,0] neg_lo:[0,1] neg_hi:[0,1]
	v_pk_fma_f32 v[106:107], v[44:45], v[114:115], v[106:107]
	v_pk_fma_f32 v[40:41], v[44:45], v[120:121], v[40:41]
	v_pk_fma_f32 v[114:115], v[68:69], v[104:105], v[106:107] op_sel_hi:[1,0,1]
	v_pk_mul_f32 v[106:107], v[62:63], v[108:109] op_sel_hi:[1,0] neg_lo:[0,1] neg_hi:[0,1]
	v_pk_fma_f32 v[120:121], v[68:69], v[104:105], v[40:41] op_sel:[0,1,0]
	v_pk_mul_f32 v[40:41], v[62:63], v[48:49] op_sel_hi:[1,0] neg_lo:[0,1] neg_hi:[0,1]
	v_pk_fma_f32 v[106:107], v[46:47], v[110:111], v[106:107]
	v_pk_fma_f32 v[40:41], v[46:47], v[98:99], v[40:41]
	v_pk_fma_f32 v[110:111], v[70:71], v[104:105], v[106:107] op_sel_hi:[1,0,1]
	v_pk_mul_f32 v[106:107], v[72:73], v[124:125]
	v_pk_mul_f32 v[108:109], v[74:75], v[112:113]
	v_pk_fma_f32 v[98:99], v[70:71], v[104:105], v[40:41] op_sel:[0,1,0]
	v_pk_mul_f32 v[40:41], v[72:73], v[116:117]
	v_pk_mul_f32 v[42:43], v[74:75], v[118:119]
	v_pk_fma_f32 v[106:107], v[76:77], v[114:115], v[106:107]
	v_pk_fma_f32 v[108:109], v[78:79], v[110:111], v[108:109]
	v_pk_fma_f32 v[40:41], v[76:77], v[120:121], v[40:41]
	v_pk_fma_f32 v[42:43], v[78:79], v[98:99], v[42:43]
	v_pk_add_f32 v[106:107], v[106:107], v[108:109]
	v_pk_add_f32 v[108:109], v[40:41], v[42:43]
	v_add_u32_e32 v130, s49, v127
	ds_read_b128 v[40:43], v130
	ds_read_b128 v[44:47], v130 offset:16
	ds_read_b128 v[48:51], v130 offset:8704
	ds_read_b128 v[52:55], v130 offset:8720
	ds_read_b128 v[56:59], v130 offset:17408
	ds_read_b128 v[60:63], v130 offset:17424
	ds_read_b128 v[64:67], v130 offset:26112
	ds_read_b128 v[68:71], v130 offset:26128
	ds_read_b128 v[72:75], v130 offset:34816
	ds_read_b128 v[76:79], v130 offset:34832
	v_add_u32_e32 v131, s49, v126
	ds_read_b64 v[104:105], v131
	s_waitcnt lgkmcnt(13)
	v_pk_mul_f32 v[126:127], v[28:29], v[124:125]
	v_pk_mul_f32 v[128:129], v[30:31], v[112:113]
	v_pk_mul_f32 v[28:29], v[28:29], v[116:117]
	v_pk_mul_f32 v[30:31], v[30:31], v[118:119]
	v_pk_fma_f32 v[126:127], v[24:25], v[114:115], v[126:127]
	v_pk_fma_f32 v[128:129], v[26:27], v[110:111], v[128:129]
	v_pk_fma_f32 v[24:25], v[24:25], v[120:121], v[28:29]
	v_pk_fma_f32 v[26:27], v[26:27], v[98:99], v[30:31]
	v_pk_add_f32 v[126:127], v[126:127], v[128:129]
	v_pk_add_f32 v[24:25], v[24:25], v[26:27]
	v_add_f32_e32 v126, v126, v127
	v_add_f32_e32 v24, v24, v25
	s_nop 0
	v_add_f32_dpp v126, v126, v126 quad_perm:[1,0,3,2] row_mask:0xf bank_mask:0xf bound_ctrl:1
	v_add_f32_dpp v24, v24, v24 quad_perm:[1,0,3,2] row_mask:0xf bank_mask:0xf bound_ctrl:1
	s_nop 0
	v_add_f32_dpp v126, v126, v126 quad_perm:[2,3,0,1] row_mask:0xf bank_mask:0xf bound_ctrl:1
	v_add_f32_dpp v24, v24, v24 quad_perm:[2,3,0,1] row_mask:0xf bank_mask:0xf bound_ctrl:1
	s_nop 0
	v_add_f32_dpp v126, v126, v126 row_half_mirror row_mask:0xf bank_mask:0xf bound_ctrl:1
	v_add_f32_dpp v24, v24, v24 row_half_mirror row_mask:0xf bank_mask:0xf bound_ctrl:1
	v_pk_mul_f32 v[128:129], v[20:21], v[126:127] op_sel_hi:[1,0] neg_lo:[0,1] neg_hi:[0,1]
	v_pk_mul_f32 v[20:21], v[20:21], v[24:25] op_sel_hi:[1,0] neg_lo:[0,1] neg_hi:[0,1]
	s_waitcnt lgkmcnt(11)
; #define SBAR() __builtin_amdgcn_sched_barrier(0)
; #define STEP(X, ii) do { ROWSTEP(X, S0, X##vv[0], yk0, ii); ROWSTEP(X, S1, X##vv[1], yk1, ii); } while (0)
; DEV void scan_job(const P& p, int job, char* shm) {
;     ...
;       f32x4 Aw0, Aw1, Aq0, Aq1, Ab0, Ab1, Ad0, Ad1, Ar0, Ar1; f32x2 Avv;
;       f32x4 Bw0, Bw1, Bq0, Bq1, Bb0, Bb1, Bd0, Bd1, Br0, Br1; f32x2 Bvv;
;       float yk0 = 0.f, yk1 = 0.f;
;       LOADOPS(A, toff);
; #pragma unroll 1
;       for (int i = 0; i < TC; i += 8) {
;         const int t8 = toff;
; #pragma unroll
;         for (int u = 0; u < 8; u += 2) {
;           toff += tstep; LOADOPS(B, toff); SBAR();
;           STEP(A, u); SBAR();
;           toff += tstep; if (i + u + 2 < TC) LOADOPS(A, toff);
	v_pk_fma_f32 v[124:125], v[36:37], v[124:125], v[128:129]
	v_pk_fma_f32 v[20:21], v[36:37], v[116:117], v[20:21]
	v_pk_fma_f32 v[124:125], v[122:123], v[12:13], v[124:125] op_sel_hi:[0,1,1]
	v_pk_fma_f32 v[116:117], v[122:123], v[12:13], v[20:21] op_sel:[1,0,0]
	v_pk_mul_f32 v[12:13], v[22:23], v[24:25] op_sel_hi:[1,0] neg_lo:[0,1] neg_hi:[0,1]
	v_pk_mul_f32 v[128:129], v[22:23], v[126:127] op_sel_hi:[1,0] neg_lo:[0,1] neg_hi:[0,1]
	v_pk_fma_f32 v[12:13], v[38:39], v[118:119], v[12:13]
	v_pk_fma_f32 v[112:113], v[38:39], v[112:113], v[128:129]
	v_pk_mul_f32 v[128:129], v[16:17], v[126:127] op_sel_hi:[1,0] neg_lo:[0,1] neg_hi:[0,1]
	v_pk_fma_f32 v[118:119], v[122:123], v[14:15], v[12:13] op_sel:[1,0,0]
	v_pk_mul_f32 v[12:13], v[16:17], v[24:25] op_sel_hi:[1,0] neg_lo:[0,1] neg_hi:[0,1]
	v_pk_fma_f32 v[114:115], v[32:33], v[114:115], v[128:129]
	v_pk_fma_f32 v[12:13], v[32:33], v[120:121], v[12:13]
	v_pk_fma_f32 v[114:115], v[122:123], v[8:9], v[114:115] op_sel_hi:[0,1,1]
	v_pk_mul_f32 v[126:127], v[18:19], v[126:127] op_sel_hi:[1,0] neg_lo:[0,1] neg_hi:[0,1]
	v_pk_fma_f32 v[120:121], v[122:123], v[8:9], v[12:13] op_sel:[1,0,0]
	v_pk_mul_f32 v[8:9], v[18:19], v[24:25] op_sel_hi:[1,0] neg_lo:[0,1] neg_hi:[0,1]
	v_pk_fma_f32 v[112:113], v[122:123], v[14:15], v[112:113] op_sel_hi:[0,1,1]
	v_pk_fma_f32 v[110:111], v[34:35], v[110:111], v[126:127]
	v_pk_fma_f32 v[8:9], v[34:35], v[98:99], v[8:9]
	v_pk_fma_f32 v[110:111], v[122:123], v[10:11], v[110:111] op_sel_hi:[0,1,1]
	v_pk_mul_f32 v[126:127], v[4:5], v[124:125]
	v_pk_mul_f32 v[128:129], v[6:7], v[112:113]
	v_pk_fma_f32 v[122:123], v[122:123], v[10:11], v[8:9] op_sel:[1,0,0]
	v_pk_mul_f32 v[4:5], v[4:5], v[116:117]
	v_pk_mul_f32 v[6:7], v[6:7], v[118:119]
	v_pk_fma_f32 v[126:127], v[0:1], v[114:115], v[126:127]
	v_pk_fma_f32 v[128:129], v[2:3], v[110:111], v[128:129]
	v_pk_fma_f32 v[0:1], v[0:1], v[120:121], v[4:5]
	v_pk_fma_f32 v[2:3], v[2:3], v[122:123], v[6:7]
	v_pk_add_f32 v[126:127], v[126:127], v[128:129]
	v_pk_add_f32 v[128:129], v[0:1], v[2:3]
	v_add_u32_e32 v161, s49, v131
	v_add_u32_e32 v170, s49, v130
	ds_read_b64 v[98:99], v161
	ds_read_b128 v[4:7], v170 offset:34832
	ds_read_b128 v[16:19], v170 offset:34816
	ds_read_b128 v[12:15], v170 offset:26128
	ds_read_b128 v[20:23], v170 offset:26112
	ds_read_b128 v[8:11], v170 offset:17424
	ds_read_b128 v[24:27], v170 offset:17408
	ds_read_b128 v[32:35], v170 offset:8720
	ds_read_b128 v[36:39], v170 offset:8704
	ds_read_b128 v[0:3], v170 offset:16
	ds_read_b128 v[28:31], v170
	s_waitcnt lgkmcnt(14)
	v_pk_mul_f32 v[130:131], v[48:49], v[124:125]
	v_pk_mul_f32 v[132:133], v[50:51], v[112:113]
	v_pk_mul_f32 v[48:49], v[48:49], v[116:117]
	v_pk_mul_f32 v[50:51], v[50:51], v[118:119]
	v_pk_fma_f32 v[130:131], v[52:53], v[114:115], v[130:131]
	v_pk_fma_f32 v[132:133], v[54:55], v[110:111], v[132:133]
	v_pk_fma_f32 v[48:49], v[52:53], v[120:121], v[48:49]
	v_pk_fma_f32 v[50:51], v[54:55], v[122:123], v[50:51]
	v_pk_add_f32 v[130:131], v[130:131], v[132:133]
	v_pk_add_f32 v[48:49], v[48:49], v[50:51]
	v_add_f32_e32 v130, v130, v131
	v_add_f32_e32 v48, v48, v49
	s_nop 0
	v_add_f32_dpp v130, v130, v130 quad_perm:[1,0,3,2] row_mask:0xf bank_mask:0xf bound_ctrl:1
	v_add_f32_dpp v48, v48, v48 quad_perm:[1,0,3,2] row_mask:0xf bank_mask:0xf bound_ctrl:1
	s_nop 0
	v_add_f32_dpp v130, v130, v130 quad_perm:[2,3,0,1] row_mask:0xf bank_mask:0xf bound_ctrl:1
	v_add_f32_dpp v48, v48, v48 quad_perm:[2,3,0,1] row_mask:0xf bank_mask:0xf bound_ctrl:1
	s_nop 0
	v_add_f32_dpp v130, v130, v130 row_half_mirror row_mask:0xf bank_mask:0xf bound_ctrl:1
	v_add_f32_dpp v48, v48, v48 row_half_mirror row_mask:0xf bank_mask:0xf bound_ctrl:1
	v_pk_mul_f32 v[132:133], v[56:57], v[130:131] op_sel_hi:[1,0] neg_lo:[0,1] neg_hi:[0,1]
	v_pk_mul_f32 v[50:51], v[56:57], v[48:49] op_sel_hi:[1,0] neg_lo:[0,1] neg_hi:[0,1]
	v_pk_fma_f32 v[124:125], v[40:41], v[124:125], v[132:133]
	v_pk_fma_f32 v[40:41], v[40:41], v[116:117], v[50:51]
	v_pk_mul_f32 v[132:133], v[58:59], v[130:131] op_sel_hi:[1,0] neg_lo:[0,1] neg_hi:[0,1]
	s_waitcnt lgkmcnt(11)
	v_pk_fma_f32 v[134:135], v[64:65], v[104:105], v[40:41] op_sel:[0,1,0]
	v_pk_mul_f32 v[40:41], v[58:59], v[48:49] op_sel_hi:[1,0] neg_lo:[0,1] neg_hi:[0,1]
	v_pk_fma_f32 v[112:113], v[42:43], v[112:113], v[132:133]
	v_pk_fma_f32 v[40:41], v[42:43], v[118:119], v[40:41]
	v_pk_mul_f32 v[132:133], v[60:61], v[130:131] op_sel_hi:[1,0] neg_lo:[0,1] neg_hi:[0,1]
	v_pk_fma_f32 v[136:137], v[66:67], v[104:105], v[40:41] op_sel:[0,1,0]
	v_pk_mul_f32 v[40:41], v[60:61], v[48:49] op_sel_hi:[1,0] neg_lo:[0,1] neg_hi:[0,1]
	v_pk_mul_f32 v[130:131], v[62:63], v[130:131] op_sel_hi:[1,0] neg_lo:[0,1] neg_hi:[0,1]
	v_pk_fma_f32 v[40:41], v[44:45], v[120:121], v[40:41]
	v_pk_fma_f32 v[124:125], v[64:65], v[104:105], v[124:125] op_sel_hi:[1,0,1]
	v_pk_fma_f32 v[112:113], v[66:67], v[104:105], v[112:113] op_sel_hi:[1,0,1]
	v_pk_fma_f32 v[114:115], v[44:45], v[114:115], v[132:133]
	v_pk_fma_f32 v[110:111], v[46:47], v[110:111], v[130:131]
	v_pk_fma_f32 v[162:163], v[68:69], v[104:105], v[40:41] op_sel:[0,1,0]
	v_pk_mul_f32 v[40:41], v[62:63], v[48:49] op_sel_hi:[1,0] neg_lo:[0,1] neg_hi:[0,1]
	v_pk_fma_f32 v[114:115], v[68:69], v[104:105], v[114:115] op_sel_hi:[1,0,1]
	v_pk_fma_f32 v[130:131], v[70:71], v[104:105], v[110:111] op_sel_hi:[1,0,1]
	v_pk_mul_f32 v[110:111], v[72:73], v[124:125]
	v_pk_mul_f32 v[132:133], v[74:75], v[112:113]
	v_pk_fma_f32 v[40:41], v[46:47], v[122:123], v[40:41]
	v_pk_fma_f32 v[110:111], v[76:77], v[114:115], v[110:111]
	v_pk_fma_f32 v[132:133], v[78:79], v[130:131], v[132:133]
	v_pk_fma_f32 v[166:167], v[70:71], v[104:105], v[40:41] op_sel:[0,1,0]
	v_pk_mul_f32 v[40:41], v[72:73], v[134:135]
	v_pk_mul_f32 v[42:43], v[74:75], v[136:137]
	v_pk_add_f32 v[132:133], v[110:111], v[132:133]
	v_pk_fma_f32 v[40:41], v[76:77], v[162:163], v[40:41]
	v_pk_fma_f32 v[42:43], v[78:79], v[166:167], v[42:43]
	s_nop 0
	v_pk_add_f32 v[168:169], v[40:41], v[42:43]
	v_add_u32_e32 v44, s49, v170
	ds_read_b128 v[52:55], v44
	ds_read_b128 v[40:43], v44 offset:16
	ds_read_b128 v[76:79], v44 offset:8704
	ds_read_b128 v[72:75], v44 offset:8720
	ds_read_b128 v[64:67], v44 offset:17408
	ds_read_b128 v[56:59], v44 offset:17424
	ds_read_b128 v[68:71], v44 offset:26112
	ds_read_b128 v[60:63], v44 offset:26128
	ds_read_b128 v[48:51], v44 offset:34816
	ds_read_b128 v[44:47], v44 offset:34832
	v_add_u32_e32 v104, s49, v161
	ds_read_b64 v[104:105], v104
	s_waitcnt lgkmcnt(13)
; #define SBAR() __builtin_amdgcn_sched_barrier(0)
; #define STEP(X, ii) do { ROWSTEP(X, S0, X##vv[0], yk0, ii); ROWSTEP(X, S1, X##vv[1], yk1, ii); } while (0)
; DEV void scan_job(const P& p, int job, char* shm) {
;     ...
;       f32x4 Aw0, Aw1, Aq0, Aq1, Ab0, Ab1, Ad0, Ad1, Ar0, Ar1; f32x2 Avv;
;       f32x4 Bw0, Bw1, Bq0, Bq1, Bb0, Bb1, Bd0, Bd1, Br0, Br1; f32x2 Bvv;
;       float yk0 = 0.f, yk1 = 0.f;
;       LOADOPS(A, toff);
; #pragma unroll 1
;       for (int i = 0; i < TC; i += 8) {
;         const int t8 = toff;
; #pragma unroll
;         for (int u = 0; u < 8; u += 2) {
;           toff += tstep; LOADOPS(B, toff); SBAR();
;           STEP(A, u); SBAR();
;           toff += tstep; if (i + u + 2 < TC) LOADOPS(A, toff);
;           SBAR();
;           STEP(B, u + 1); SBAR();
;         }
;         *reinterpret_cast<f32x2*>(Yy + t8 + np * tstep + 2 * rp) = f32x2{yk0, yk1};
	v_pk_mul_f32 v[110:111], v[36:37], v[124:125]
	v_pk_mul_f32 v[116:117], v[38:39], v[112:113]
	v_pk_fma_f32 v[110:111], v[32:33], v[114:115], v[110:111]
	v_pk_fma_f32 v[116:117], v[34:35], v[130:131], v[116:117]
	s_nop 0
	v_pk_add_f32 v[110:111], v[110:111], v[116:117]
	s_nop 0
	v_add_f32_e32 v110, v110, v111
	s_nop 1
	v_add_f32_dpp v110, v110, v110 quad_perm:[1,0,3,2] row_mask:0xf bank_mask:0xf bound_ctrl:1
	s_nop 0
	s_nop 0
	v_add_f32_dpp v110, v110, v110 quad_perm:[2,3,0,1] row_mask:0xf bank_mask:0xf bound_ctrl:1
	s_nop 1
	v_add_f32_dpp v116, v110, v110 row_half_mirror row_mask:0xf bank_mask:0xf bound_ctrl:1
	v_pk_mul_f32 v[110:111], v[24:25], v[116:117] op_sel_hi:[1,0] neg_lo:[0,1] neg_hi:[0,1]
	v_pk_mul_f32 v[118:119], v[26:27], v[116:117] op_sel_hi:[1,0] neg_lo:[0,1] neg_hi:[0,1]
	s_waitcnt lgkmcnt(11)
	v_pk_fma_f32 v[110:111], v[28:29], v[124:125], v[110:111]
	v_pk_fma_f32 v[112:113], v[30:31], v[112:113], v[118:119]
	v_pk_mul_f32 v[118:119], v[8:9], v[116:117] op_sel_hi:[1,0] neg_lo:[0,1] neg_hi:[0,1]
	v_pk_mul_f32 v[116:117], v[10:11], v[116:117] op_sel_hi:[1,0] neg_lo:[0,1] neg_hi:[0,1]
	v_pk_fma_f32 v[110:111], v[98:99], v[20:21], v[110:111] op_sel_hi:[0,1,1]
	v_pk_fma_f32 v[112:113], v[98:99], v[22:23], v[112:113] op_sel_hi:[0,1,1]
	v_pk_fma_f32 v[114:115], v[0:1], v[114:115], v[118:119]
	v_pk_fma_f32 v[116:117], v[2:3], v[130:131], v[116:117]
	v_pk_fma_f32 v[114:115], v[98:99], v[12:13], v[114:115] op_sel_hi:[0,1,1]
	v_pk_fma_f32 v[116:117], v[98:99], v[14:15], v[116:117] op_sel_hi:[0,1,1]
	v_pk_mul_f32 v[118:119], v[16:17], v[110:111]
	v_pk_mul_f32 v[120:121], v[18:19], v[112:113]
	v_pk_fma_f32 v[118:119], v[4:5], v[114:115], v[118:119]
	v_pk_fma_f32 v[120:121], v[6:7], v[116:117], v[120:121]
	s_nop 0
	v_pk_add_f32 v[170:171], v[118:119], v[120:121]
	v_pk_mul_f32 v[118:119], v[36:37], v[134:135]
	v_pk_mul_f32 v[120:121], v[38:39], v[136:137]
	v_pk_fma_f32 v[118:119], v[32:33], v[162:163], v[118:119]
	v_pk_fma_f32 v[120:121], v[34:35], v[166:167], v[120:121]
	s_nop 0
	v_pk_add_f32 v[118:119], v[118:119], v[120:121]
	s_nop 0
	v_add_f32_e32 v118, v118, v119
	s_nop 1
	v_add_f32_dpp v118, v118, v118 quad_perm:[1,0,3,2] row_mask:0xf bank_mask:0xf bound_ctrl:1
	s_nop 1
	v_add_f32_dpp v118, v118, v118 quad_perm:[2,3,0,1] row_mask:0xf bank_mask:0xf bound_ctrl:1
	s_nop 1
	v_add_f32_dpp v124, v118, v118 row_half_mirror row_mask:0xf bank_mask:0xf bound_ctrl:1
	v_pk_mul_f32 v[118:119], v[24:25], v[124:125] op_sel_hi:[1,0] neg_lo:[0,1] neg_hi:[0,1]
	v_pk_mul_f32 v[120:121], v[26:27], v[124:125] op_sel_hi:[1,0] neg_lo:[0,1] neg_hi:[0,1]
	v_pk_fma_f32 v[118:119], v[28:29], v[134:135], v[118:119]
	v_pk_fma_f32 v[120:121], v[30:31], v[136:137], v[120:121]
	v_pk_mul_f32 v[122:123], v[8:9], v[124:125] op_sel_hi:[1,0] neg_lo:[0,1] neg_hi:[0,1]
	v_pk_mul_f32 v[124:125], v[10:11], v[124:125] op_sel_hi:[1,0] neg_lo:[0,1] neg_hi:[0,1]
	v_pk_fma_f32 v[118:119], v[98:99], v[20:21], v[118:119] op_sel:[1,0,0]
	v_pk_fma_f32 v[120:121], v[98:99], v[22:23], v[120:121] op_sel:[1,0,0]
	v_pk_fma_f32 v[122:123], v[0:1], v[162:163], v[122:123]
	v_pk_fma_f32 v[124:125], v[2:3], v[166:167], v[124:125]
	v_pk_fma_f32 v[122:123], v[98:99], v[12:13], v[122:123] op_sel:[1,0,0]
	v_pk_fma_f32 v[124:125], v[98:99], v[14:15], v[124:125] op_sel:[1,0,0]
	v_pk_mul_f32 v[130:131], v[16:17], v[118:119]
	v_pk_mul_f32 v[134:135], v[18:19], v[120:121]
	v_pk_fma_f32 v[130:131], v[4:5], v[122:123], v[130:131]
	v_pk_fma_f32 v[134:135], v[6:7], v[124:125], v[134:135]
	v_mov_b32_e32 v136, v170
	v_pk_add_f32 v[134:135], v[130:131], v[134:135]
	v_add_f32_e32 v94, v94, v95
	v_add_f32_e32 v95, v96, v97
	v_add_f32_e32 v100, v100, v101
	v_add_f32_e32 v101, v102, v103
	v_add_f32_e32 v106, v106, v107
	v_add_f32_e32 v107, v108, v109
	v_add_f32_e32 v126, v126, v127
	v_add_f32_e32 v127, v128, v129
	v_mov_b32_e32 v130, v132
	v_mov_b32_e32 v131, v168
	v_mov_b32_e32 v168, v133
	v_mov_b32_e32 v137, v134
	v_mov_b32_e32 v134, v171
	v_pk_add_f32 v[130:131], v[130:131], v[168:169]
	v_pk_add_f32 v[134:135], v[136:137], v[134:135]
	s_add_i32 s40, s45, 14
	s_cmp_gt_u32 s40, 29
	s_cbranch_scc1 .LBB0_1506
	ds_read_b128 v[0:3], v159 offset:16
	ds_read_b128 v[36:39], v159 offset:8704
	ds_read_b128 v[32:35], v159 offset:8720
	ds_read_b128 v[24:27], v159 offset:17408
	ds_read_b128 v[8:11], v159 offset:17424
	ds_read_b128 v[20:23], v159 offset:26112
	ds_read_b128 v[12:15], v159 offset:26128
	ds_read_b128 v[28:31], v159
	ds_read_b128 v[4:7], v159 offset:34832
	v_add_u32_e32 v98, s34, v157
	ds_read_b128 v[16:19], v159 offset:34816
	ds_read_b64 v[98:99], v98
	s_branch .LBB0_1506

; __global__ void __launch_bounds__(512) mega(P p) {
;   __shared__ __attribute__((aligned(1024))) char shm[SHM_DECL];
	.amdhsa_kernel _Z4mega1P
		.amdhsa_group_segment_fixed_size 163840
		.amdhsa_private_segment_fixed_size 0
		.amdhsa_kernarg_size 504
		.amdhsa_user_sgpr_count 2
		.amdhsa_user_sgpr_dispatch_ptr 0
		.amdhsa_user_sgpr_queue_ptr 0
		.amdhsa_user_sgpr_kernarg_segment_ptr 1
		.amdhsa_user_sgpr_dispatch_id 0
		.amdhsa_user_sgpr_kernarg_preload_length 0
		.amdhsa_user_sgpr_kernarg_preload_offset 0
		.amdhsa_user_sgpr_private_segment_size 0
		.amdhsa_uses_dynamic_stack 0
		.amdhsa_enable_private_segment 0
		.amdhsa_system_sgpr_workgroup_id_x 1
		.amdhsa_system_sgpr_workgroup_id_y 0
		.amdhsa_system_sgpr_workgroup_id_z 0
		.amdhsa_system_sgpr_workgroup_info 0
		.amdhsa_system_vgpr_workitem_id 2
		.amdhsa_next_free_vgpr 248
		.amdhsa_next_free_sgpr 102
		.amdhsa_accum_offset 248
		.amdhsa_reserve_vcc 1
		.amdhsa_float_round_mode_32 0
		.amdhsa_float_round_mode_16_64 0
		.amdhsa_float_denorm_mode_32 3
		.amdhsa_float_denorm_mode_16_64 3
		.amdhsa_dx10_clamp 1
		.amdhsa_ieee_mode 1
		.amdhsa_fp16_overflow 0
		.amdhsa_tg_split 0
		.amdhsa_exception_fp_ieee_invalid_op 0
		.amdhsa_exception_fp_denorm_src 0
		.amdhsa_exception_fp_ieee_div_zero 0
		.amdhsa_exception_fp_ieee_overflow 0
		.amdhsa_exception_fp_ieee_underflow 0
		.amdhsa_exception_fp_ieee_inexact 0
		.amdhsa_exception_int_div_zero 0
	.end_amdhsa_kernel

; __global__ void __launch_bounds__(512) mega(P p) {
;   __shared__ __attribute__((aligned(1024))) char shm[SHM_DECL];
amdhsa.kernels:
  - .agpr_count:     0
    .args:
      - .offset:         0
        .size:           248
        .value_kind:     by_value
      - .offset:         248
        .size:           4
        .value_kind:     hidden_block_count_x
      - .offset:         252
        .size:           4
        .value_kind:     hidden_block_count_y
      - .offset:         256
        .size:           4
        .value_kind:     hidden_block_count_z
      - .offset:         260
        .size:           2
        .value_kind:     hidden_group_size_x
      - .offset:         262
        .size:           2
        .value_kind:     hidden_group_size_y
      - .offset:         264
        .size:           2
        .value_kind:     hidden_group_size_z
      - .offset:         266
        .size:           2
        .value_kind:     hidden_remainder_x
      - .offset:         268
        .size:           2
        .value_kind:     hidden_remainder_y
      - .offset:         270
        .size:           2
        .value_kind:     hidden_remainder_z
      - .offset:         288
        .size:           8
        .value_kind:     hidden_global_offset_x
      - .offset:         296
        .size:           8
        .value_kind:     hidden_global_offset_y
      - .offset:         304
        .size:           8
        .value_kind:     hidden_global_offset_z
      - .offset:         312
        .size:           2
        .value_kind:     hidden_grid_dims
      - .offset:         336
        .size:           8
        .value_kind:     hidden_multigrid_sync_arg
    .group_segment_fixed_size: 163840
    .kernarg_segment_align: 8
    .kernarg_segment_size: 504
    .language:       OpenCL C
    .language_version:
      - 2
      - 0
    .max_flat_workgroup_size: 512
    .name:           _Z4mega1P
    .private_segment_fixed_size: 0
    .sgpr_count:     108
    .sgpr_spill_count: 86
    .symbol:         _Z4mega1P.kd
    .uniform_work_group_size: 1
    .uses_dynamic_stack: false
    .vgpr_count:     248
    .vgpr_spill_count: 0
    .wavefront_size: 64
